# P9 stops rewriting x1 (67MB of f32 stores removed); stores row sum+rstd; P11 epilogue recomputes x1 from h1 with identical f32 ops
# speedup vs baseline: 1.0043x; 1.0043x over previous
; __global__ void __launch_bounds__(512, 2) fwd_kernel(Args a) {
;     ...
;         for (int m = 2 * gw; m < MTOK; m += 2 * NGW) {
;             const float* md = mod + (size_t)(m >> 12) * NADA; f32x4* xr = (f32x4*)(out + (size_t)m * DMODEL) + lane;
;             f32x4 va[8], vb[8]; float sa = 0.f, sb = 0.f;
; #pragma unroll
;             for (int j = 0; j < 8; ++j) { va[j] = __builtin_nontemporal_load(xr + 64 * j); vb[j] = __builtin_nontemporal_load(xr + 512 + 64 * j); }
; #pragma unroll
;             for (int j = 0; j < 8; ++j) { sa += (va[j][0] + va[j][1]) + (va[j][2] + va[j][3]); sb += (vb[j][0] + vb[j][1]) + (vb[j][2] + vb[j][3]); }
;             const float mean_a = wave_sum(sa) * (1.0f / DMODEL), mean_b = wave_sum(sb) * (1.0f / DMODEL); float qa = 0.f, qb_ = 0.f;
.LBB0_963:
	v_add_co_u32_e32 v138, vcc, 0xffffd000, v134
	global_load_dwordx4 v[34:37], v[134:135], off offset:-4096 nt
	global_load_dwordx4 v[26:29], v[134:135], off offset:-3072 nt
	v_addc_co_u32_e32 v139, vcc, -1, v135, vcc
	v_add_co_u32_e32 v140, vcc, 0xfffff000, v134
	global_load_dwordx4 v[58:61], v[138:139], off offset:-3072 nt
	global_load_dwordx4 v[50:53], v[138:139], off offset:-2048 nt
	global_load_dwordx4 v[42:45], v[138:139], off offset:-1024 nt
	v_addc_co_u32_e32 v141, vcc, -1, v135, vcc
	global_load_dwordx4 v[38:41], v[138:139], off nt
	global_load_dwordx4 v[62:65], v[140:141], off offset:-3072 nt
	global_load_dwordx4 v[54:57], v[140:141], off offset:-2048 nt
	global_load_dwordx4 v[46:49], v[140:141], off offset:-1024 nt
	v_add_co_u32_e32 v136, vcc, 0xffffe000, v134
	s_ashr_i32 s0, s8, 12
	s_nop 0
	v_addc_co_u32_e32 v137, vcc, -1, v135, vcc
	global_load_dwordx4 v[30:33], v[136:137], off offset:-3072 nt
	global_load_dwordx4 v[22:25], v[136:137], off offset:-2048 nt
	global_load_dwordx4 v[18:21], v[134:135], off offset:-2048 nt
	global_load_dwordx4 v[14:17], v[136:137], off offset:-1024 nt
	global_load_dwordx4 v[10:13], v[134:135], off offset:-1024 nt
	global_load_dwordx4 v[6:9], v[136:137], off nt
	global_load_dwordx4 v[2:5], v[134:135], off nt
	s_mul_hi_i32 s1, s0, 0xc000
	s_mul_i32 s0, s0, 0xc000
	s_add_u32 s2, s18, s0
	s_addc_u32 s3, s19, s1
	s_add_u32 s14, s2, 0x6000
	s_addc_u32 s15, s3, 0
	s_add_u32 s16, s2, 0x8000
	s_addc_u32 s17, s3, 0
	s_add_i32 s8, s8, s6
	s_cmpk_lt_i32 s8, 0x2000
	s_waitcnt vmcnt(0)
	v_add_f32_e32 v66, v34, v35
	v_add_f32_e32 v68, v36, v37
	v_mov_b32_e32 v67, v28
	v_mov_b32_e32 v69, v29
	v_pk_add_f32 v[66:67], v[66:67], v[68:69]
	v_mov_b32_e32 v68, v58
	v_mov_b32_e32 v69, v50
	v_mov_b32_e32 v72, v59
	v_mov_b32_e32 v73, v51
	v_mov_b32_e32 v74, v60
	v_mov_b32_e32 v75, v52
	v_mov_b32_e32 v76, v61
	v_mov_b32_e32 v77, v53
	v_mov_b32_e32 v78, v43
	v_mov_b32_e32 v79, v44
	v_mov_b32_e32 v80, v42
	v_mov_b32_e32 v81, v45
	v_pk_add_f32 v[68:69], v[68:69], v[72:73]
	v_pk_add_f32 v[72:73], v[74:75], v[76:77]
	v_mov_b32_e32 v74, v62
	v_mov_b32_e32 v75, v54
	v_mov_b32_e32 v76, v63
	v_mov_b32_e32 v77, v55
	v_mov_b32_e32 v86, v64
	v_mov_b32_e32 v87, v56
	v_mov_b32_e32 v88, v65
	v_mov_b32_e32 v89, v57
	v_pk_add_f32 v[78:79], v[78:79], v[80:81]
	v_mov_b32_e32 v80, v47
	v_mov_b32_e32 v81, v48
	v_mov_b32_e32 v90, v46
	v_mov_b32_e32 v91, v49
	v_pk_add_f32 v[68:69], v[68:69], v[72:73]
	v_pk_add_f32 v[72:73], v[74:75], v[76:77]
	v_pk_add_f32 v[74:75], v[86:87], v[88:89]
	v_pk_add_f32 v[76:77], v[78:79], v[78:79] op_sel:[0,1] op_sel_hi:[1,0]
	v_pk_add_f32 v[78:79], v[80:81], v[90:91]
	v_add_f32_e32 v68, 0, v68
	v_pk_add_f32 v[72:73], v[72:73], v[74:75]
	v_pk_add_f32 v[74:75], v[78:79], v[78:79] op_sel:[0,1] op_sel_hi:[1,0]
	v_add_f32_e32 v80, v68, v69
	v_add_f32_e32 v68, 0, v72
	v_mov_b32_e32 v71, v26
	v_mov_b32_e32 v75, v27
	v_add_f32_e32 v70, v68, v73
	v_add_f32_e32 v82, v38, v39
	v_add_f32_e32 v84, v40, v41
	v_mov_b32_e32 v81, v30
	v_mov_b32_e32 v83, v32
	v_mov_b32_e32 v85, v33
	v_mov_b32_e32 v77, v31
	v_pk_add_f32 v[70:71], v[70:71], v[74:75]
	v_mov_b32_e32 v86, v23
	v_mov_b32_e32 v87, v24
	v_pk_add_f32 v[78:79], v[82:83], v[84:85]
	v_pk_add_f32 v[68:69], v[80:81], v[76:77]
	v_pk_add_f32 v[66:67], v[70:71], v[66:67]
	v_mov_b32_e32 v70, v22
	v_mov_b32_e32 v71, v25
	v_pk_add_f32 v[68:69], v[68:69], v[78:79]
	v_pk_add_f32 v[70:71], v[86:87], v[70:71]
	v_pk_add_f32 v[68:69], v[68:69], v[68:69] op_sel:[0,1] op_sel_hi:[1,0]
	v_pk_add_f32 v[70:71], v[70:71], v[70:71] op_sel:[0,1] op_sel_hi:[1,0]
	v_mov_b32_e32 v72, v19
	v_mov_b32_e32 v73, v20
	v_mov_b32_e32 v74, v18
	v_mov_b32_e32 v75, v21
	v_pk_add_f32 v[72:73], v[72:73], v[74:75]
	v_add_f32_e32 v74, v14, v15
	v_add_f32_e32 v76, v16, v17
	v_mov_b32_e32 v69, v6
	v_mov_b32_e32 v71, v7
	v_mov_b32_e32 v75, v8
	v_mov_b32_e32 v77, v9
	v_pk_add_f32 v[66:67], v[66:67], v[66:67] op_sel:[0,1] op_sel_hi:[1,0]
	v_pk_add_f32 v[72:73], v[72:73], v[72:73] op_sel:[0,1] op_sel_hi:[1,0]
	v_pk_add_f32 v[68:69], v[68:69], v[70:71]
	v_pk_add_f32 v[70:71], v[74:75], v[76:77]
	v_add_f32_e32 v78, v10, v11
	v_add_f32_e32 v80, v12, v13
	v_pk_add_f32 v[68:69], v[68:69], v[70:71]
	v_mov_b32_e32 v67, v2
	v_mov_b32_e32 v73, v3
	v_mov_b32_e32 v79, v4
	v_mov_b32_e32 v81, v5
	v_add_f32_e32 v70, v68, v69
	v_pk_add_f32 v[66:67], v[66:67], v[72:73]
	v_pk_add_f32 v[68:69], v[78:79], v[80:81]
	s_nop 0
	v_pk_add_f32 v[66:67], v[66:67], v[68:69]
	ds_bpermute_b32 v68, v1, v70
	v_add_f32_e32 v66, v66, v67
	ds_bpermute_b32 v67, v1, v66
	s_waitcnt lgkmcnt(1)
	v_add_f32_e32 v68, v70, v68
	ds_bpermute_b32 v69, v153, v68
	s_waitcnt lgkmcnt(1)
	v_add_f32_e32 v66, v66, v67
	ds_bpermute_b32 v67, v153, v66
	s_waitcnt lgkmcnt(1)
	v_add_f32_e32 v68, v68, v69
	ds_bpermute_b32 v69, v155, v68
	s_waitcnt lgkmcnt(1)
	v_add_f32_e32 v66, v66, v67
	ds_bpermute_b32 v67, v155, v66
	s_waitcnt lgkmcnt(1)
	v_add_f32_e32 v68, v68, v69
	ds_bpermute_b32 v69, v158, v68
	s_waitcnt lgkmcnt(1)
	v_add_f32_e32 v66, v66, v67
	ds_bpermute_b32 v67, v158, v66
	s_waitcnt lgkmcnt(1)
	v_add_f32_e32 v68, v68, v69
	ds_bpermute_b32 v69, v159, v68
	s_waitcnt lgkmcnt(1)
	v_add_f32_e32 v66, v66, v67
	ds_bpermute_b32 v67, v159, v66
	s_waitcnt lgkmcnt(1)
	v_add_f32_e32 v68, v68, v69
	ds_bpermute_b32 v69, v160, v68
	s_waitcnt lgkmcnt(1)
	v_add_f32_e32 v66, v66, v67
	ds_bpermute_b32 v67, v160, v66
	s_waitcnt lgkmcnt(1)
	v_add_f32_e32 v70, v68, v69
	v_mov_b32_e32 v240, v70
	v_fmamk_f32 v59, v70, 0xba000000, v59
	s_waitcnt lgkmcnt(0)
; __global__ void __launch_bounds__(512, 2) fwd_kernel(Args a) {
;     ...
;             const float mean_a = wave_sum(sa) * (1.0f / DMODEL), mean_b = wave_sum(sb) * (1.0f / DMODEL); float qa = 0.f, qb_ = 0.f;
; #pragma unroll
;             for (int j = 0; j < 8; ++j) { va[j] = va[j] - mean_a; vb[j] = vb[j] - mean_b;
;                 qa += (va[j][0] * va[j][0] + va[j][1] * va[j][1]) + (va[j][2] * va[j][2] + va[j][3] * va[j][3]);
;                 qb_ += (vb[j][0] * vb[j][0] + vb[j][1] * vb[j][1]) + (vb[j][2] * vb[j][2] + vb[j][3] * vb[j][3]); }
;             const float rstd_a = 1.0f / sqrtf(wave_sum(qa) * (1.0f / DMODEL) + LN_EPS), rstd_b = 1.0f / sqrtf(wave_sum(qb_) * (1.0f / DMODEL) + LN_EPS);
	v_add_f32_e32 v71, v66, v67
	v_mov_b32_e32 v241, v71
	v_fmamk_f32 v51, v70, 0xba000000, v51
	v_fmamk_f32 v69, v70, 0xba000000, v61
	v_fmac_f32_e32 v58, 0xba000000, v70
	v_fmamk_f32 v149, v70, 0xba000000, v53
	v_fmac_f32_e32 v50, 0xba000000, v70
	v_fmamk_f32 v145, v71, 0xba000000, v57
	v_fmamk_f32 v144, v71, 0xba000000, v56
	v_mov_b32_e32 v56, v59
	v_mov_b32_e32 v57, v51
	v_fmamk_f32 v68, v70, 0xba000000, v60
	v_fmamk_f32 v61, v71, 0xba000000, v65
	v_fmamk_f32 v60, v71, 0xba000000, v64
	v_fmamk_f32 v148, v70, 0xba000000, v52
	v_mov_b32_e32 v52, v58
	v_mov_b32_e32 v53, v50
	v_pk_mul_f32 v[56:57], v[56:57], v[56:57]
	v_mov_b32_e32 v64, v69
	v_mov_b32_e32 v65, v149
	v_fmamk_f32 v63, v71, 0xba000000, v63
	v_fmamk_f32 v55, v71, 0xba000000, v55
	v_pk_fma_f32 v[52:53], v[52:53], v[52:53], v[56:57]
	v_mov_b32_e32 v56, v68
	v_mov_b32_e32 v57, v148
	v_pk_mul_f32 v[64:65], v[64:65], v[64:65]
	v_fmac_f32_e32 v62, 0xba000000, v71
	v_fmac_f32_e32 v54, 0xba000000, v71
	v_pk_fma_f32 v[56:57], v[56:57], v[56:57], v[64:65]
	v_mov_b32_e32 v64, v63
	v_mov_b32_e32 v65, v55
	v_pk_add_f32 v[56:57], v[52:53], v[56:57]
	v_mov_b32_e32 v52, v62
	v_mov_b32_e32 v53, v54
	v_pk_mul_f32 v[64:65], v[64:65], v[64:65]
	v_mov_b32_e32 v66, v61
	v_mov_b32_e32 v67, v145
	v_pk_fma_f32 v[52:53], v[52:53], v[52:53], v[64:65]
	v_mov_b32_e32 v64, v60
	v_mov_b32_e32 v65, v144
	v_pk_mul_f32 v[66:67], v[66:67], v[66:67]
	v_fmamk_f32 v151, v70, 0xba000000, v43
	v_fmamk_f32 v150, v70, 0xba000000, v42
	v_fmamk_f32 v45, v70, 0xba000000, v45
	v_fmac_f32_e32 v44, 0xba000000, v70
	v_pk_fma_f32 v[64:65], v[64:65], v[64:65], v[66:67]
	v_fmamk_f32 v147, v71, 0xba000000, v47
	v_fmamk_f32 v146, v71, 0xba000000, v46
	v_pk_mul_f32 v[42:43], v[44:45], v[44:45]
	v_pk_mul_f32 v[46:47], v[150:151], v[150:151]
	v_pk_add_f32 v[64:65], v[52:53], v[64:65]
	v_fmamk_f32 v49, v71, 0xba000000, v49
	v_fmac_f32_e32 v48, 0xba000000, v71
	v_pk_mov_b32 v[52:53], v[46:47], v[42:43] op_sel:[1,0]
	v_mov_b32_e32 v47, v43
	v_pk_add_f32 v[42:43], v[52:53], v[46:47]
	v_pk_mul_f32 v[46:47], v[48:49], v[48:49]
	v_pk_mul_f32 v[52:53], v[146:147], v[146:147]
	v_fmac_f32_e32 v30, 0xba000000, v70
	v_pk_mov_b32 v[66:67], v[52:53], v[46:47] op_sel:[1,0]
	v_mov_b32_e32 v53, v47
	v_pk_add_f32 v[46:47], v[66:67], v[52:53]
	v_fmamk_f32 v143, v70, 0xba000000, v39
	v_fmamk_f32 v142, v70, 0xba000000, v38
	v_fmamk_f32 v52, v71, 0xba000000, v34
	v_fmamk_f32 v39, v70, 0xba000000, v33
	v_fmamk_f32 v38, v70, 0xba000000, v32
	v_fmamk_f32 v31, v70, 0xba000000, v31
	v_mul_f32_e32 v34, v30, v30
	v_pk_add_f32 v[32:33], v[56:57], v[56:57] op_sel:[0,1] op_sel_hi:[1,0]
	v_fmamk_f32 v53, v71, 0xba000000, v35
	v_mul_f32_e32 v66, v31, v31
	v_mov_b32_e32 v33, v34
	v_pk_add_f32 v[34:35], v[42:43], v[42:43] op_sel:[0,1] op_sel_hi:[1,0]
	v_fmamk_f32 v41, v70, 0xba000000, v41
	v_mov_b32_e32 v35, v66
	v_fmac_f32_e32 v40, 0xba000000, v70
	v_pk_add_f32 v[32:33], v[32:33], v[34:35]
	v_mul_f32_e32 v34, v143, v143
	v_mul_f32_e32 v42, v41, v41
	v_mul_f32_e32 v67, v38, v38
	v_mul_f32_e32 v72, v39, v39
	v_pk_fma_f32 v[34:35], v[142:143], v[142:143], v[34:35] op_sel_hi:[1,1,0]
	v_pk_fma_f32 v[42:43], v[40:41], v[40:41], v[42:43] op_sel_hi:[1,1,0]
	v_mov_b32_e32 v35, v67
	v_mov_b32_e32 v43, v72
	v_fmac_f32_e32 v26, 0xba000000, v71
	v_pk_add_f32 v[34:35], v[34:35], v[42:43]
	v_fmamk_f32 v27, v71, 0xba000000, v27
	v_pk_add_f32 v[32:33], v[32:33], v[34:35]
	v_mul_f32_e32 v42, v26, v26
	v_pk_add_f32 v[34:35], v[64:65], v[64:65] op_sel:[0,1] op_sel_hi:[1,0]
	v_mul_f32_e32 v56, v27, v27
	v_mov_b32_e32 v35, v42
	v_pk_add_f32 v[42:43], v[46:47], v[46:47] op_sel:[0,1] op_sel_hi:[1,0]
	v_fmamk_f32 v37, v71, 0xba000000, v37
	v_mov_b32_e32 v43, v56
	v_fmac_f32_e32 v36, 0xba000000, v71
	v_fmamk_f32 v29, v71, 0xba000000, v29
	v_fmamk_f32 v28, v71, 0xba000000, v28
	v_pk_add_f32 v[34:35], v[34:35], v[42:43]
	v_mul_f32_e32 v42, v53, v53
	v_mul_f32_e32 v46, v37, v37
	v_mul_f32_e32 v57, v28, v28
	v_mul_f32_e32 v66, v29, v29
	v_pk_fma_f32 v[42:43], v[52:53], v[52:53], v[42:43] op_sel_hi:[1,1,0]
	v_pk_fma_f32 v[46:47], v[36:37], v[36:37], v[46:47] op_sel_hi:[1,1,0]
	v_mov_b32_e32 v43, v57
	v_mov_b32_e32 v47, v66
	v_pk_add_f32 v[42:43], v[42:43], v[46:47]
	v_fmamk_f32 v47, v70, 0xba000000, v23
	v_fmamk_f32 v46, v70, 0xba000000, v22
	v_fmamk_f32 v25, v70, 0xba000000, v25
	v_fmac_f32_e32 v24, 0xba000000, v70
	v_pk_add_f32 v[34:35], v[34:35], v[42:43]
	v_fmamk_f32 v43, v71, 0xba000000, v19
	v_fmamk_f32 v42, v71, 0xba000000, v18
	v_pk_mul_f32 v[18:19], v[24:25], v[24:25]
	v_pk_mul_f32 v[22:23], v[46:47], v[46:47]
	v_fmamk_f32 v21, v71, 0xba000000, v21
	v_fmac_f32_e32 v20, 0xba000000, v71
	v_pk_mov_b32 v[56:57], v[22:23], v[18:19] op_sel:[1,0]
	v_mov_b32_e32 v23, v19
	v_pk_add_f32 v[56:57], v[56:57], v[22:23]
	v_pk_mul_f32 v[18:19], v[20:21], v[20:21]
	v_pk_mul_f32 v[22:23], v[42:43], v[42:43]
	v_fmac_f32_e32 v6, 0xba000000, v70
	v_pk_mov_b32 v[64:65], v[22:23], v[18:19] op_sel:[1,0]
	v_mov_b32_e32 v23, v19
	v_pk_add_f32 v[64:65], v[64:65], v[22:23]
	v_fmamk_f32 v23, v70, 0xba000000, v15
	v_fmamk_f32 v22, v70, 0xba000000, v14
	v_fmamk_f32 v18, v71, 0xba000000, v10
	v_fmamk_f32 v15, v70, 0xba000000, v9
	v_fmamk_f32 v14, v70, 0xba000000, v8
	v_fmamk_f32 v7, v70, 0xba000000, v7
	v_mul_f32_e32 v10, v6, v6
	v_pk_add_f32 v[8:9], v[32:33], v[32:33] op_sel:[0,1] op_sel_hi:[1,0]
	v_fmamk_f32 v19, v71, 0xba000000, v11
	v_mul_f32_e32 v66, v7, v7
	v_mov_b32_e32 v9, v10
	v_pk_add_f32 v[10:11], v[56:57], v[56:57] op_sel:[0,1] op_sel_hi:[1,0]
	v_fmamk_f32 v17, v70, 0xba000000, v17
	v_mov_b32_e32 v11, v66
	v_fmac_f32_e32 v16, 0xba000000, v70
	v_pk_add_f32 v[8:9], v[8:9], v[10:11]
	v_mul_f32_e32 v10, v23, v23
	v_mul_f32_e32 v32, v17, v17
	v_mul_f32_e32 v67, v14, v14
	v_mul_f32_e32 v70, v15, v15
	v_pk_fma_f32 v[10:11], v[22:23], v[22:23], v[10:11] op_sel_hi:[1,1,0]
	v_pk_fma_f32 v[32:33], v[16:17], v[16:17], v[32:33] op_sel_hi:[1,1,0]
	v_mov_b32_e32 v11, v67
	v_mov_b32_e32 v33, v70
	v_pk_add_f32 v[10:11], v[10:11], v[32:33]
	v_fmac_f32_e32 v2, 0xba000000, v71
	v_pk_add_f32 v[8:9], v[8:9], v[10:11]
	v_fmamk_f32 v3, v71, 0xba000000, v3
	v_add_f32_e32 v32, v8, v9
	v_pk_add_f32 v[8:9], v[34:35], v[34:35] op_sel:[0,1] op_sel_hi:[1,0]
	ds_bpermute_b32 v34, v1, v32
	v_mul_f32_e32 v10, v2, v2
	v_mul_f32_e32 v33, v3, v3
	v_mov_b32_e32 v9, v10
	v_pk_add_f32 v[10:11], v[64:65], v[64:65] op_sel:[0,1] op_sel_hi:[1,0]
	v_fmamk_f32 v13, v71, 0xba000000, v13
	v_mov_b32_e32 v11, v33
	s_waitcnt lgkmcnt(0)
; __device__ __forceinline__ unsigned cvt_pk_bf16(float lo, float hi) { unsigned r; asm volatile("v_cvt_pk_bf16_f32 %0, %1, %2" : "=v"(r) : "v"(lo), "v"(hi)); return r; }
; __global__ void __launch_bounds__(512, 2) fwd_kernel(Args a) {
;     ...
;             const float rstd_a = 1.0f / sqrtf(wave_sum(qa) * (1.0f / DMODEL) + LN_EPS), rstd_b = 1.0f / sqrtf(wave_sum(qb_) * (1.0f / DMODEL) + LN_EPS);
;             u32x2* o8 = (u32x2*)(ubuf + (size_t)m * DMODEL) + lane;
;             f32x4 ggv[8], bbv[8], shv[8], scv[8];
; #pragma unroll
;             for (int j = 0; j < 8; ++j) { const int col = 4 * lane + 256 * j; ggv[j] = *(const f32x4*)(lng_p + col); bbv[j] = *(const f32x4*)(lnb_p + col);
;                 shv[j] = *(const f32x4*)(md + 3 * DMODEL + col); scv[j] = *(const f32x4*)(md + 4 * DMODEL + col); }
; #pragma unroll
;             for (int j = 0; j < 8; ++j) { const f32x4 gg = ggv[j], bb = bbv[j];
;                 const f32x4 ya = va[j] * rstd_a * gg + bb, yb = vb[j] * rstd_b * gg + bb; __builtin_nontemporal_store(ya, xr + 64 * j); __builtin_nontemporal_store(yb, xr + 512 + 64 * j);
;                 const f32x4 sh = shv[j], sc = scv[j] + 1.0f;
;                 const f32x4 ua = ya * sc + sh, ub = yb * sc + sh; u32x2 wa, wb;
;                 wa.x = pg8::cvt_pk_bf16(ua[0], ua[1]); wa.y = pg8::cvt_pk_bf16(ua[2], ua[3]); wb.x = pg8::cvt_pk_bf16(ub[0], ub[1]); wb.y = pg8::cvt_pk_bf16(ub[2], ub[3]);
;                 o8[64 * j] = wa; o8[512 + 64 * j] = wb; } }
	v_add_f32_e32 v33, v32, v34
	ds_bpermute_b32 v34, v153, v33
	v_fmac_f32_e32 v12, 0xba000000, v71
	v_fmamk_f32 v5, v71, 0xba000000, v5
	v_fmamk_f32 v4, v71, 0xba000000, v4
	v_pk_add_f32 v[8:9], v[8:9], v[10:11]
	v_mul_f32_e32 v10, v19, v19
	v_mul_f32_e32 v32, v13, v13
	v_mul_f32_e32 v56, v4, v4
	v_mul_f32_e32 v57, v5, v5
	v_pk_fma_f32 v[10:11], v[18:19], v[18:19], v[10:11] op_sel_hi:[1,1,0]
	s_waitcnt lgkmcnt(0)
	v_add_f32_e32 v34, v33, v34
	v_pk_fma_f32 v[32:33], v[12:13], v[12:13], v[32:33] op_sel_hi:[1,1,0]
	v_mov_b32_e32 v11, v56
	v_mov_b32_e32 v33, v57
	v_pk_add_f32 v[10:11], v[10:11], v[32:33]
	ds_bpermute_b32 v35, v155, v34
	v_pk_add_f32 v[8:9], v[8:9], v[10:11]
	s_waitcnt lgkmcnt(0)
	v_add_f32_e32 v10, v34, v35
	v_add_f32_e32 v8, v8, v9
	ds_bpermute_b32 v9, v1, v8
	ds_bpermute_b32 v11, v158, v10
	s_waitcnt lgkmcnt(1)
	v_add_f32_e32 v8, v8, v9
	ds_bpermute_b32 v9, v153, v8
	s_waitcnt lgkmcnt(1)
	v_add_f32_e32 v10, v10, v11
	ds_bpermute_b32 v11, v159, v10
	s_waitcnt lgkmcnt(1)
	v_add_f32_e32 v8, v8, v9
	ds_bpermute_b32 v9, v155, v8
	s_waitcnt lgkmcnt(1)
	v_add_f32_e32 v10, v10, v11
	ds_bpermute_b32 v11, v160, v10
	s_waitcnt lgkmcnt(1)
	v_add_f32_e32 v8, v8, v9
	ds_bpermute_b32 v9, v158, v8
	s_waitcnt lgkmcnt(1)
	v_add_f32_e32 v10, v10, v11
	v_fmamk_f32 v10, v10, 0x3a000000, v161
	v_mul_f32_e32 v11, 0x4f800000, v10
	v_cmp_gt_f32_e32 vcc, s9, v10
	s_waitcnt lgkmcnt(0)
	v_add_f32_e32 v8, v8, v9
	ds_bpermute_b32 v9, v159, v8
	v_cndmask_b32_e32 v56, v10, v11, vcc
	v_sqrt_f32_e32 v10, v56
	s_waitcnt lgkmcnt(0)
	v_add_f32_e32 v8, v8, v9
	ds_bpermute_b32 v9, v160, v8
	v_add_u32_e32 v11, -1, v10
	v_fma_f32 v32, -v11, v10, v56
	v_cmp_ge_f32_e64 s[0:1], 0, v32
	v_add_u32_e32 v64, 1, v10
	s_waitcnt lgkmcnt(0)
	v_add_f32_e32 v8, v8, v9
	v_cndmask_b32_e64 v57, v10, v11, s[0:1]
	v_fma_f32 v65, -v64, v10, v56
	v_fmamk_f32 v66, v8, 0x3a000000, v161
	global_load_dwordx4 v[8:11], v[112:113], off
	global_load_dwordx4 v[32:35], v[114:115], off
	v_mul_f32_e32 v67, 0x4f800000, v66
	v_cmp_gt_f32_e64 s[0:1], s9, v66
	v_cmp_lt_f32_e64 s[2:3], 0, v65
	global_load_dwordx4 v[172:175], v163, s[14:15]
	global_load_dwordx4 v[176:179], v163, s[16:17]
	v_cndmask_b32_e64 v66, v66, v67, s[0:1]
	v_sqrt_f32_e32 v67, v66
	v_cndmask_b32_e64 v57, v57, v64, s[2:3]
	v_mul_f32_e32 v64, 0x37800000, v57
	v_cndmask_b32_e32 v57, v57, v64, vcc
	v_add_u32_e32 v64, -1, v67
	v_fma_f32 v65, -v64, v67, v66
	v_cmp_ge_f32_e32 vcc, 0, v65
	v_add_u32_e32 v65, 1, v67
	global_load_dwordx4 v[180:183], v[112:113], off offset:1024
	global_load_dwordx4 v[184:187], v[114:115], off offset:1024
	v_cndmask_b32_e32 v64, v67, v64, vcc
	v_fma_f32 v67, -v65, v67, v66
	v_cmp_lt_f32_e32 vcc, 0, v67
	global_load_dwordx4 v[188:191], v164, s[14:15]
	global_load_dwordx4 v[192:195], v164, s[16:17]
	v_cndmask_b32_e32 v64, v64, v65, vcc
	v_mul_f32_e32 v65, 0x37800000, v64
	v_cndmask_b32_e64 v64, v64, v65, s[0:1]
	v_cmp_class_f32_e32 vcc, v66, v162
	global_load_dwordx4 v[198:201], v165, s[14:15]
	global_load_dwordx4 v[202:205], v165, s[16:17]
	global_load_dwordx4 v[206:209], v[112:113], off offset:2048
	global_load_dwordx4 v[210:213], v[112:113], off offset:3072
	global_load_dwordx4 v[214:217], v[114:115], off offset:2048
	global_load_dwordx4 v[218:221], v[114:115], off offset:3072
	global_load_dwordx4 v[222:225], v166, s[14:15]
	global_load_dwordx4 v[226:229], v166, s[16:17]
	global_load_dwordx4 v[104:107], v[116:117], off
	global_load_dwordx4 v[108:111], v[118:119], off
	global_load_dwordx4 v[96:99], v167, s[14:15]
	global_load_dwordx4 v[100:103], v167, s[16:17]
	global_load_dwordx4 v[84:87], v[120:121], off
	global_load_dwordx4 v[88:91], v[122:123], off
	v_cndmask_b32_e32 v64, v64, v66, vcc
	v_div_scale_f32 v65, s[0:1], v64, v64, 1.0
	v_rcp_f32_e32 v66, v65
	v_cmp_class_f32_e32 vcc, v56, v162
	s_waitcnt vmcnt(18)
	v_pk_add_f32 v[156:157], v[178:179], 1.0 op_sel_hi:[1,0]
	v_cndmask_b32_e32 v56, v57, v56, vcc
	v_fma_f32 v57, -v65, v66, 1.0
	v_fmac_f32_e32 v66, v57, v66
	v_div_scale_f32 v57, vcc, 1.0, v64, 1.0
	v_mul_f32_e32 v67, v57, v66
	v_fma_f32 v70, -v65, v67, v57
	v_fmac_f32_e32 v67, v70, v66
	v_fma_f32 v57, -v65, v67, v57
	v_div_fmas_f32 v57, v57, v66, v67
	v_div_fixup_f32 v152, v57, v64, 1.0
	v_div_scale_f32 v57, s[0:1], v56, v56, 1.0
	v_rcp_f32_e32 v70, v57
	global_load_dwordx4 v[80:83], v168, s[14:15]
	global_load_dwordx4 v[92:95], v168, s[16:17]
	global_load_dwordx4 v[64:67], v[124:125], off
	v_pk_add_f32 v[176:177], v[176:177], 1.0 op_sel_hi:[1,0]
	v_pk_mul_f32 v[48:49], v[152:153], v[48:49] op_sel_hi:[0,1]
	v_fma_f32 v71, -v57, v70, 1.0
	v_fmac_f32_e32 v70, v71, v70
	v_div_scale_f32 v71, vcc, 1.0, v56, 1.0
	v_mul_f32_e32 v76, v71, v70
	v_fma_f32 v72, -v57, v76, v71
	v_fmac_f32_e32 v76, v72, v70
	v_fma_f32 v57, -v57, v76, v71
	v_div_fmas_f32 v57, v57, v70, v76
	v_div_fixup_f32 v154, v57, v56, 1.0
	global_load_dwordx4 v[72:75], v[126:127], off
	v_pk_mul_f32 v[56:57], v[154:155], v[58:59] op_sel_hi:[0,1]
	v_pk_mul_f32 v[58:59], v[154:155], v[68:69] op_sel_hi:[0,1]
	v_pk_fma_f32 v[232:233], v[10:11], v[58:59], v[34:35]
	v_pk_fma_f32 v[230:231], v[8:9], v[56:57], v[32:33]
	v_pk_mul_f32 v[56:57], v[152:153], v[62:63] op_sel_hi:[0,1]
	v_pk_mul_f32 v[58:59], v[152:153], v[60:61] op_sel_hi:[0,1]
	v_pk_fma_f32 v[236:237], v[10:11], v[58:59], v[34:35]
	v_pk_fma_f32 v[234:235], v[8:9], v[56:57], v[32:33]
	global_load_dwordx4 v[68:71], v169, s[14:15]
	global_load_dwordx4 v[76:79], v169, s[16:17]
	global_load_dwordx4 v[32:35], v[128:129], off
	global_load_dwordx4 v[60:63], v[130:131], off
	global_load_dwordx4 v[8:11], v170, s[14:15]
	global_load_dwordx4 v[56:59], v170, s[16:17]
	v_pk_fma_f32 v[178:179], v[232:233], v[156:157], v[174:175]
	v_pk_fma_f32 v[156:157], v[236:237], v[156:157], v[174:175]
	v_pk_fma_f32 v[230:231], v[230:231], v[176:177], v[172:173]
	v_pk_fma_f32 v[172:173], v[234:235], v[176:177], v[172:173]
	v_cvt_pk_bf16_f32 v174, v230, v231
	v_cvt_pk_bf16_f32 v175, v178, v179
	v_pk_mul_f32 v[50:51], v[154:155], v[50:51] op_sel_hi:[0,1]
	v_cvt_pk_bf16_f32 v172, v172, v173
	v_cvt_pk_bf16_f32 v173, v156, v157
	v_add_co_u32_e32 v156, vcc, s7, v132
	v_pk_mul_f32 v[148:149], v[154:155], v[148:149] op_sel_hi:[0,1]
	s_nop 0
	v_addc_co_u32_e32 v157, vcc, -1, v133, vcc
	global_store_dwordx2 v[156:157], v[174:175], off offset:-3584
	global_store_dwordx2 v[132:133], v[172:173], off offset:-3584
	s_waitcnt vmcnt(28)
; __device__ __forceinline__ unsigned cvt_pk_bf16(float lo, float hi) { unsigned r; asm volatile("v_cvt_pk_bf16_f32 %0, %1, %2" : "=v"(r) : "v"(lo), "v"(hi)); return r; }
; __global__ void __launch_bounds__(512, 2) fwd_kernel(Args a) {
;     ...
;             for (int j = 0; j < 8; ++j) { const f32x4 gg = ggv[j], bb = bbv[j];
;                 const f32x4 ya = va[j] * rstd_a * gg + bb, yb = vb[j] * rstd_b * gg + bb; __builtin_nontemporal_store(ya, xr + 64 * j); __builtin_nontemporal_store(yb, xr + 512 + 64 * j);
;                 const f32x4 sh = shv[j], sc = scv[j] + 1.0f;
;                 const f32x4 ua = ya * sc + sh, ub = yb * sc + sh; u32x2 wa, wb;
;                 wa.x = pg8::cvt_pk_bf16(ua[0], ua[1]); wa.y = pg8::cvt_pk_bf16(ua[2], ua[3]); wb.x = pg8::cvt_pk_bf16(ub[0], ub[1]); wb.y = pg8::cvt_pk_bf16(ub[2], ub[3]);
;                 o8[64 * j] = wa; o8[512 + 64 * j] = wb; } }
	v_pk_fma_f32 v[172:173], v[180:181], v[50:51], v[184:185]
	v_pk_mul_f32 v[50:51], v[152:153], v[54:55] op_sel_hi:[0,1]
	v_pk_mul_f32 v[54:55], v[152:153], v[144:145] op_sel_hi:[0,1]
	v_pk_fma_f32 v[174:175], v[182:183], v[148:149], v[186:187]
	v_pk_fma_f32 v[178:179], v[182:183], v[54:55], v[186:187]
	v_pk_fma_f32 v[176:177], v[180:181], v[50:51], v[184:185]
	s_waitcnt vmcnt(26)
	v_pk_add_f32 v[50:51], v[194:195], 1.0 op_sel_hi:[1,0]
	v_pk_add_f32 v[54:55], v[192:193], 1.0 op_sel_hi:[1,0]
	v_pk_fma_f32 v[144:145], v[174:175], v[50:51], v[190:191]
	v_pk_fma_f32 v[148:149], v[172:173], v[54:55], v[188:189]
	v_pk_fma_f32 v[50:51], v[178:179], v[50:51], v[190:191]
	v_pk_fma_f32 v[54:55], v[176:177], v[54:55], v[188:189]
	v_pk_mul_f32 v[44:45], v[154:155], v[44:45] op_sel_hi:[0,1]
	v_cvt_pk_bf16_f32 v148, v148, v149
	v_cvt_pk_bf16_f32 v149, v144, v145
	v_cvt_pk_bf16_f32 v54, v54, v55
	v_cvt_pk_bf16_f32 v55, v50, v51
	v_pk_mul_f32 v[50:51], v[154:155], v[150:151] op_sel_hi:[0,1]
	s_waitcnt vmcnt(21)
	v_pk_fma_f32 v[150:151], v[208:209], v[44:45], v[216:217]
	v_pk_mul_f32 v[44:45], v[152:153], v[146:147] op_sel_hi:[0,1]
	global_store_dwordx2 v[156:157], v[148:149], off offset:-3072
	global_store_dwordx2 v[132:133], v[54:55], off offset:-3072
	v_pk_fma_f32 v[148:149], v[206:207], v[50:51], v[214:215]
	v_pk_fma_f32 v[50:51], v[208:209], v[48:49], v[216:217]
	v_pk_fma_f32 v[48:49], v[206:207], v[44:45], v[214:215]
	v_pk_add_f32 v[44:45], v[204:205], 1.0 op_sel_hi:[1,0]
	v_pk_add_f32 v[54:55], v[202:203], 1.0 op_sel_hi:[1,0]
	v_pk_fma_f32 v[140:141], v[150:151], v[44:45], v[200:201]
	v_pk_fma_f32 v[144:145], v[148:149], v[54:55], v[198:199]
	v_pk_fma_f32 v[44:45], v[50:51], v[44:45], v[200:201]
	v_pk_fma_f32 v[48:49], v[48:49], v[54:55], v[198:199]
	v_cvt_pk_bf16_f32 v50, v144, v145
	v_cvt_pk_bf16_f32 v51, v140, v141
	v_pk_mul_f32 v[40:41], v[154:155], v[40:41] op_sel_hi:[0,1]
	v_cvt_pk_bf16_f32 v48, v48, v49
	v_cvt_pk_bf16_f32 v49, v44, v45
	global_store_dwordx2 v[156:157], v[50:51], off offset:-2560
	global_store_dwordx2 v[132:133], v[48:49], off offset:-2560
	v_pk_mul_f32 v[44:45], v[154:155], v[142:143] op_sel_hi:[0,1]
	s_waitcnt vmcnt(24)
	v_pk_fma_f32 v[50:51], v[212:213], v[40:41], v[220:221]
	v_pk_mul_f32 v[40:41], v[152:153], v[52:53] op_sel_hi:[0,1]
	v_pk_mul_f32 v[36:37], v[152:153], v[36:37] op_sel_hi:[0,1]
	v_pk_fma_f32 v[48:49], v[210:211], v[44:45], v[218:219]
	v_pk_fma_f32 v[54:55], v[212:213], v[36:37], v[220:221]
	v_pk_fma_f32 v[52:53], v[210:211], v[40:41], v[218:219]
	s_waitcnt vmcnt(22)
	v_pk_add_f32 v[36:37], v[228:229], 1.0 op_sel_hi:[1,0]
	v_pk_add_f32 v[40:41], v[226:227], 1.0 op_sel_hi:[1,0]
	v_pk_fma_f32 v[44:45], v[50:51], v[36:37], v[224:225]
	v_pk_fma_f32 v[48:49], v[48:49], v[40:41], v[222:223]
	v_pk_fma_f32 v[36:37], v[54:55], v[36:37], v[224:225]
	v_pk_fma_f32 v[40:41], v[52:53], v[40:41], v[222:223]
	v_cvt_pk_bf16_f32 v48, v48, v49
	v_cvt_pk_bf16_f32 v49, v44, v45
	v_pk_mul_f32 v[30:31], v[154:155], v[30:31] op_sel_hi:[0,1]
	v_cvt_pk_bf16_f32 v40, v40, v41
	v_cvt_pk_bf16_f32 v41, v36, v37
	v_pk_mul_f32 v[36:37], v[154:155], v[38:39] op_sel_hi:[0,1]
	v_pk_mul_f32 v[26:27], v[152:153], v[26:27] op_sel_hi:[0,1]
	v_pk_mul_f32 v[28:29], v[152:153], v[28:29] op_sel_hi:[0,1]
	global_store_dwordx2 v[156:157], v[48:49], off offset:-2048
	global_store_dwordx2 v[132:133], v[40:41], off offset:-2048
	s_waitcnt vmcnt(22)
	v_pk_fma_f32 v[38:39], v[106:107], v[36:37], v[110:111]
	v_pk_fma_f32 v[36:37], v[104:105], v[30:31], v[108:109]
	v_pk_fma_f32 v[28:29], v[106:107], v[28:29], v[110:111]
	v_pk_fma_f32 v[26:27], v[104:105], v[26:27], v[108:109]
	s_waitcnt vmcnt(20)
; __device__ __forceinline__ unsigned cvt_pk_bf16(float lo, float hi) { unsigned r; asm volatile("v_cvt_pk_bf16_f32 %0, %1, %2" : "=v"(r) : "v"(lo), "v"(hi)); return r; }
; __global__ void __launch_bounds__(512, 2) fwd_kernel(Args a) {
;     ...
;             for (int j = 0; j < 8; ++j) { const f32x4 gg = ggv[j], bb = bbv[j];
;                 const f32x4 ya = va[j] * rstd_a * gg + bb, yb = vb[j] * rstd_b * gg + bb; __builtin_nontemporal_store(ya, xr + 64 * j); __builtin_nontemporal_store(yb, xr + 512 + 64 * j);
;                 const f32x4 sh = shv[j], sc = scv[j] + 1.0f;
;                 const f32x4 ua = ya * sc + sh, ub = yb * sc + sh; u32x2 wa, wb;
;                 wa.x = pg8::cvt_pk_bf16(ua[0], ua[1]); wa.y = pg8::cvt_pk_bf16(ua[2], ua[3]); wb.x = pg8::cvt_pk_bf16(ub[0], ub[1]); wb.y = pg8::cvt_pk_bf16(ub[2], ub[3]);
;                 o8[64 * j] = wa; o8[512 + 64 * j] = wb; } }
	v_pk_add_f32 v[30:31], v[102:103], 1.0 op_sel_hi:[1,0]
	v_pk_add_f32 v[40:41], v[100:101], 1.0 op_sel_hi:[1,0]
	v_pk_mul_f32 v[24:25], v[154:155], v[24:25] op_sel_hi:[0,1]
	v_pk_fma_f32 v[38:39], v[38:39], v[30:31], v[98:99]
	v_pk_fma_f32 v[28:29], v[28:29], v[30:31], v[98:99]
	v_pk_fma_f32 v[26:27], v[26:27], v[40:41], v[96:97]
	v_pk_fma_f32 v[36:37], v[36:37], v[40:41], v[96:97]
	v_pk_mul_f32 v[20:21], v[152:153], v[20:21] op_sel_hi:[0,1]
	v_cvt_pk_bf16_f32 v30, v36, v37
	v_cvt_pk_bf16_f32 v31, v38, v39
	v_cvt_pk_bf16_f32 v26, v26, v27
	v_cvt_pk_bf16_f32 v27, v28, v29
	v_pk_mul_f32 v[28:29], v[154:155], v[46:47] op_sel_hi:[0,1]
	global_store_dwordx2 v[156:157], v[30:31], off offset:-1536
	global_store_dwordx2 v[132:133], v[26:27], off offset:-1536
	s_waitcnt vmcnt(20)
	v_pk_fma_f32 v[26:27], v[86:87], v[24:25], v[90:91]
	v_pk_fma_f32 v[24:25], v[84:85], v[28:29], v[88:89]
	v_pk_mul_f32 v[28:29], v[152:153], v[42:43] op_sel_hi:[0,1]
	v_pk_fma_f32 v[30:31], v[86:87], v[20:21], v[90:91]
	s_waitcnt vmcnt(18)
	v_pk_add_f32 v[20:21], v[94:95], 1.0 op_sel_hi:[1,0]
	v_pk_add_f32 v[36:37], v[92:93], 1.0 op_sel_hi:[1,0]
	v_pk_fma_f32 v[28:29], v[84:85], v[28:29], v[88:89]
	v_pk_mul_f32 v[16:17], v[154:155], v[16:17] op_sel_hi:[0,1]
	v_pk_fma_f32 v[26:27], v[26:27], v[20:21], v[82:83]
	v_pk_fma_f32 v[24:25], v[24:25], v[36:37], v[80:81]
	v_pk_fma_f32 v[20:21], v[30:31], v[20:21], v[82:83]
	v_pk_fma_f32 v[28:29], v[28:29], v[36:37], v[80:81]
	v_cvt_pk_bf16_f32 v24, v24, v25
	v_cvt_pk_bf16_f32 v25, v26, v27
	v_pk_mul_f32 v[12:13], v[152:153], v[12:13] op_sel_hi:[0,1]
	v_cvt_pk_bf16_f32 v26, v28, v29
	v_cvt_pk_bf16_f32 v27, v20, v21
	v_pk_mul_f32 v[20:21], v[154:155], v[22:23] op_sel_hi:[0,1]
	s_waitcnt vmcnt(16)
	v_pk_fma_f32 v[22:23], v[66:67], v[16:17], v[74:75]
	v_pk_mul_f32 v[16:17], v[152:153], v[18:19] op_sel_hi:[0,1]
	global_store_dwordx2 v[156:157], v[24:25], off offset:-1024
	global_store_dwordx2 v[132:133], v[26:27], off offset:-1024
	v_pk_fma_f32 v[20:21], v[64:65], v[20:21], v[72:73]
	v_pk_fma_f32 v[18:19], v[66:67], v[12:13], v[74:75]
	v_pk_fma_f32 v[16:17], v[64:65], v[16:17], v[72:73]
	s_waitcnt vmcnt(16)
	v_pk_add_f32 v[12:13], v[78:79], 1.0 op_sel_hi:[1,0]
	v_pk_add_f32 v[24:25], v[76:77], 1.0 op_sel_hi:[1,0]
	v_pk_mul_f32 v[6:7], v[154:155], v[6:7] op_sel_hi:[0,1]
	v_pk_fma_f32 v[22:23], v[22:23], v[12:13], v[70:71]
	v_pk_fma_f32 v[12:13], v[18:19], v[12:13], v[70:71]
	v_pk_fma_f32 v[16:17], v[16:17], v[24:25], v[68:69]
	v_pk_fma_f32 v[20:21], v[20:21], v[24:25], v[68:69]
	v_pk_mul_f32 v[2:3], v[152:153], v[2:3] op_sel_hi:[0,1]
	v_cvt_pk_bf16_f32 v18, v20, v21
	v_cvt_pk_bf16_f32 v19, v22, v23
	v_cvt_pk_bf16_f32 v16, v16, v17
	v_cvt_pk_bf16_f32 v17, v12, v13
	v_pk_mul_f32 v[12:13], v[154:155], v[14:15] op_sel_hi:[0,1]
	v_pk_mul_f32 v[4:5], v[152:153], v[4:5] op_sel_hi:[0,1]
	global_store_dwordx2 v[156:157], v[18:19], off offset:-512
	global_store_dwordx2 v[132:133], v[16:17], off offset:-512
	s_waitcnt vmcnt(16)
	v_pk_fma_f32 v[14:15], v[34:35], v[12:13], v[62:63]
	v_pk_fma_f32 v[12:13], v[32:33], v[6:7], v[60:61]
	v_pk_fma_f32 v[4:5], v[34:35], v[4:5], v[62:63]
	v_pk_fma_f32 v[2:3], v[32:33], v[2:3], v[60:61]
	s_waitcnt vmcnt(14)
	v_pk_add_f32 v[6:7], v[58:59], 1.0 op_sel_hi:[1,0]
	v_pk_add_f32 v[16:17], v[56:57], 1.0 op_sel_hi:[1,0]
	v_lshl_add_u64 v[134:135], v[134:135], 0, s[12:13]
	v_pk_fma_f32 v[14:15], v[14:15], v[6:7], v[10:11]
	v_pk_fma_f32 v[12:13], v[12:13], v[16:17], v[8:9]
	v_pk_fma_f32 v[4:5], v[4:5], v[6:7], v[10:11]
	v_pk_fma_f32 v[2:3], v[2:3], v[16:17], v[8:9]
	v_cvt_pk_bf16_f32 v6, v12, v13
	v_cvt_pk_bf16_f32 v7, v14, v15
	s_nop 0
	v_cvt_pk_bf16_f32 v2, v2, v3
	v_cvt_pk_bf16_f32 v3, v4, v5
	global_store_dwordx2 v[132:133], v[6:7], off offset:-4096
	global_store_dwordx2 v[132:133], v[2:3], off
	v_lshl_add_u64 v[132:133], v[132:133], 0, s[10:11]
	v_mov_b32_e32 v242, v240
	v_mov_b32_e32 v243, v154
	v_mov_b32_e32 v244, v241
	v_mov_b32_e32 v245, v152
	v_mov_b32_e32 v246, s8
	v_subrev_u32_e32 v246, s6, v246
	v_lshlrev_b32_e32 v246, 3, v246
	v_add_u32_e32 v246, 0x110000, v246
	global_store_dwordx4 v246, v[242:245], s[18:19]
	s_cbranch_scc1 .LBB0_963

;     __device__ __forceinline__ void operator()(const Acc& acc, const Unit& u, int wr, int wc, int fr, int fq) const {
;         const int col0 = u.pn * BM + wc * 32 + 4 * fq;
;         const float* gt = gate + (size_t)((u.pm * BM) >> 12) * NADA;
;         f32x4 gvv[2][2];
; #pragma unroll
;         for (int bj = 0; bj < 2; ++bj)
; #pragma unroll
;             for (int n = 0; n < 2; ++n) gvv[bj][n] = *(const f32x4*)(gt + col0 + bj * HALF + n * 16);
; #pragma unroll
;         for (int bj = 0; bj < 2; ++bj)
; #pragma unroll
;             for (int ai = 0; ai < 2; ++ai) {
;                 f32x4 bsv[4][2];
; #pragma unroll
;                 for (int m = 0; m < 4; ++m)
; #pragma unroll
;                     for (int n = 0; n < 2; ++n) { const size_t off = (size_t)(u.pm * BM + ai * HALF + wr * 64 + m * 16 + fr) * DMODEL + col0 + bj * HALF + n * 16; bsv[m][n] = __builtin_nontemporal_load((const f32x4*)(base + off)); }
; #pragma unroll
;                 for (int m = 0; m < 4; ++m)
; #pragma unroll
;                     for (int n = 0; n < 2; ++n) { const size_t off = (size_t)(u.pm * BM + ai * HALF + wr * 64 + m * 16 + fr) * DMODEL + col0 + bj * HALF + n * 16;
;                         *(f32x4*)(out + off) = bsv[m][n] * ALPHA + gvv[bj][n] * acc[ai][bj][m][n]; } }
; __global__ void __launch_bounds__(512, 2) fwd_kernel(Args a) {
;     ...
;             for (int j = 0; j < 8; ++j) { va[j] = va[j] - mean_a; vb[j] = vb[j] - mean_b;
;                 qa += (va[j][0] * va[j][0] + va[j][1] * va[j][1]) + (va[j][2] * va[j][2] + va[j][3] * va[j][3]);
;                 qb_ += (vb[j][0] * vb[j][0] + vb[j][1] * vb[j][1]) + (vb[j][2] * vb[j][2] + vb[j][3] * vb[j][3]); }
;             const float rstd_a = 1.0f / sqrtf(wave_sum(qa) * (1.0f / DMODEL) + LN_EPS), rstd_b = 1.0f / sqrtf(wave_sum(qb_) * (1.0f / DMODEL) + LN_EPS);
;             u32x2* o8 = (u32x2*)(ubuf + (size_t)m * DMODEL) + lane;
;             f32x4 ggv[8], bbv[8], shv[8], scv[8];
; #pragma unroll
;             for (int j = 0; j < 8; ++j) { const int col = 4 * lane + 256 * j; ggv[j] = *(const f32x4*)(lng_p + col); bbv[j] = *(const f32x4*)(lnb_p + col);
;                 shv[j] = *(const f32x4*)(md + 3 * DMODEL + col); scv[j] = *(const f32x4*)(md + 4 * DMODEL + col); }
; #pragma unroll
;             for (int j = 0; j < 8; ++j) { const f32x4 gg = ggv[j], bb = bbv[j];
.LBB0_1102:
	v_lshl_or_b32 v64, s23, 8, v172
	s_ashr_i32 s15, s22, 4
	s_mul_hi_i32 s17, s15, 0xc000
	s_mul_i32 s15, s15, 0xc000
	v_ashrrev_i32_e32 v65, 31, v64
	v_lshl_add_u32 v168, s22, 8, v170
	s_add_u32 s24, s42, s15
	v_lshlrev_b64 v[164:165], 2, v[64:65]
	v_ashrrev_i32_e32 v169, 31, v168
	s_addc_u32 s25, s43, s17
	v_lshl_add_u64 v[166:167], s[4:5], 0, v[164:165]
	v_lshlrev_b64 v[210:211], 13, v[168:169]
	v_lshl_add_u64 v[64:65], s[24:25], 0, v[164:165]
	s_add_i32 s56, 0, 0x22068
	v_mov_b32_e32 v218, s56
	ds_read2_b64 v[218:221], v218 offset1:1
	s_add_i32 s56, 0, 0x220a0
	v_mov_b32_e32 v222, s56
	ds_read_b64 v[222:223], v222
	s_waitcnt lgkmcnt(0)
	v_readfirstlane_b32 s56, v218
	v_readfirstlane_b32 s57, v219
	v_readfirstlane_b32 s58, v220
	v_readfirstlane_b32 s59, v221
	v_readfirstlane_b32 s60, v222
	v_readfirstlane_b32 s61, v223
	s_add_u32 s60, s60, 0x210000
	s_addc_u32 s61, s61, 0
	v_lshl_add_u64 v[218:219], s[56:57], 0, v[164:165]
	v_lshl_add_u64 v[220:221], s[58:59], 0, v[164:165]
	global_load_dwordx4 v[224:227], v[218:219], off
	global_load_dwordx4 v[228:231], v[218:219], off offset:64
	global_load_dwordx4 v[232:235], v[218:219], off offset:512
	global_load_dwordx4 v[236:239], v[218:219], off offset:576
	global_load_dwordx4 v[240:243], v[220:221], off
	global_load_dwordx4 v[244:247], v[220:221], off offset:64
	global_load_dwordx4 v[248:251], v[220:221], off offset:512
	global_load_dwordx4 v[144:147], v[220:221], off offset:576
	v_lshlrev_b32_e32 v171, 3, v168
	global_load_dwordx2 v[148:149], v171, s[60:61]
	global_load_dwordx2 v[150:151], v171, s[60:61] offset:128
	global_load_dwordx2 v[152:153], v171, s[60:61] offset:256
	global_load_dwordx2 v[154:155], v171, s[60:61] offset:384
	global_load_dwordx2 v[252:253], v171, s[60:61] offset:1024
	global_load_dwordx2 v[174:175], v171, s[60:61] offset:1152
	global_load_dwordx2 v[222:223], v171, s[60:61] offset:1280
	global_load_dwordx2 v[220:221], v171, s[60:61] offset:1408
	v_lshl_add_u64 v[162:163], v[166:167], 0, v[210:211]
	global_load_dwordx4 v[140:143], v[64:65], off
	global_load_dwordx4 v[136:139], v[64:65], off offset:64
	global_load_dwordx4 v[68:71], v[64:65], off offset:512
	s_nop 0
	global_load_dwordx4 v[64:67], v[64:65], off offset:576
	s_nop 0
	global_load_dwordx4 v[176:179], v[162:163], off nt
	global_load_dwordx4 v[180:183], v[162:163], off offset:64 nt
	v_or_b32_e32 v156, 16, v168
	v_ashrrev_i32_e32 v157, 31, v156
	v_lshlrev_b64 v[212:213], 13, v[156:157]
	v_lshl_add_u64 v[160:161], v[166:167], 0, v[212:213]
	global_load_dwordx4 v[184:187], v[160:161], off nt
	global_load_dwordx4 v[188:191], v[160:161], off offset:64 nt
	v_or_b32_e32 v156, 32, v168
	v_ashrrev_i32_e32 v157, 31, v156
	v_lshlrev_b64 v[214:215], 13, v[156:157]
	v_lshl_add_u64 v[158:159], v[166:167], 0, v[214:215]
	global_load_dwordx4 v[192:195], v[158:159], off nt
	global_load_dwordx4 v[198:201], v[158:159], off offset:64 nt
	v_or_b32_e32 v156, 48, v168
	v_ashrrev_i32_e32 v157, 31, v156
	v_lshlrev_b64 v[216:217], 13, v[156:157]
	v_lshl_add_u64 v[156:157], v[166:167], 0, v[216:217]
	global_load_dwordx4 v[202:205], v[156:157], off nt
	global_load_dwordx4 v[206:209], v[156:157], off offset:64 nt
	s_mov_b64 s[22:23], -1
	s_andn2_b64 vcc, exec, s[2:3]
	s_waitcnt vmcnt(0)
	v_mov_b32_e32 v173, 0xba000000
	v_pk_fma_f32 v[176:177], v[148:149], v[172:173], v[176:177] op_sel:[0,1,0] op_sel_hi:[0,1,1]
	v_pk_mul_f32 v[176:177], v[176:177], v[148:149] op_sel:[0,1] op_sel_hi:[1,1]
	v_pk_fma_f32 v[176:177], v[224:225], v[176:177], v[240:241]
	v_pk_fma_f32 v[178:179], v[148:149], v[172:173], v[178:179] op_sel:[0,1,0] op_sel_hi:[0,1,1]
	v_pk_mul_f32 v[178:179], v[178:179], v[148:149] op_sel:[0,1] op_sel_hi:[1,1]
	v_pk_fma_f32 v[178:179], v[226:227], v[178:179], v[242:243]
	v_pk_mul_f32 v[176:177], v[176:177], s[12:13] op_sel_hi:[1,0]
	v_pk_mul_f32 v[178:179], v[178:179], s[12:13] op_sel_hi:[1,0]
	v_pk_fma_f32 v[176:177], v[132:133], v[140:141], v[176:177]
	v_lshl_add_u64 v[132:133], s[4:5], 0, v[210:211]
	v_pk_fma_f32 v[178:179], v[134:135], v[142:143], v[178:179]
	v_lshl_add_u64 v[132:133], v[132:133], 0, v[164:165]
	global_store_dwordx4 v[132:133], v[176:179], off
	v_pk_fma_f32 v[180:181], v[148:149], v[172:173], v[180:181] op_sel:[0,1,0] op_sel_hi:[0,1,1]
	v_pk_mul_f32 v[180:181], v[180:181], v[148:149] op_sel:[0,1] op_sel_hi:[1,1]
	v_pk_fma_f32 v[180:181], v[228:229], v[180:181], v[244:245]
	v_pk_fma_f32 v[182:183], v[148:149], v[172:173], v[182:183] op_sel:[0,1,0] op_sel_hi:[0,1,1]
	v_pk_mul_f32 v[182:183], v[182:183], v[148:149] op_sel:[0,1] op_sel_hi:[1,1]
	v_pk_fma_f32 v[182:183], v[230:231], v[182:183], v[246:247]
	v_pk_mul_f32 v[134:135], v[182:183], s[12:13] op_sel_hi:[1,0]
	s_nop 0
	v_pk_mul_f32 v[176:177], v[180:181], s[12:13] op_sel_hi:[1,0]
	v_pk_fma_f32 v[130:131], v[130:131], v[138:139], v[134:135]
	v_pk_fma_f32 v[128:129], v[128:129], v[136:137], v[176:177]
	global_store_dwordx4 v[132:133], v[128:131], off offset:64
	s_nop 1
	v_pk_fma_f32 v[184:185], v[150:151], v[172:173], v[184:185] op_sel:[0,1,0] op_sel_hi:[0,1,1]
	v_pk_mul_f32 v[184:185], v[184:185], v[150:151] op_sel:[0,1] op_sel_hi:[1,1]
	v_pk_fma_f32 v[184:185], v[224:225], v[184:185], v[240:241]
	v_pk_fma_f32 v[186:187], v[150:151], v[172:173], v[186:187] op_sel:[0,1,0] op_sel_hi:[0,1,1]
	v_pk_mul_f32 v[186:187], v[186:187], v[150:151] op_sel:[0,1] op_sel_hi:[1,1]
	v_pk_fma_f32 v[186:187], v[226:227], v[186:187], v[242:243]
	v_pk_mul_f32 v[128:129], v[186:187], s[12:13] op_sel_hi:[1,0]
	v_pk_mul_f32 v[130:131], v[184:185], s[12:13] op_sel_hi:[1,0]
	v_pk_fma_f32 v[128:129], v[126:127], v[142:143], v[128:129]
	v_pk_fma_f32 v[126:127], v[124:125], v[140:141], v[130:131]
;     __device__ __forceinline__ void operator()(const Acc& acc, const Unit& u, int wr, int wc, int fr, int fq) const {
;     ...
;                 for (int m = 0; m < 4; ++m)
; #pragma unroll
;                     for (int n = 0; n < 2; ++n) { const size_t off = (size_t)(u.pm * BM + ai * HALF + wr * 64 + m * 16 + fr) * DMODEL + col0 + bj * HALF + n * 16; bsv[m][n] = __builtin_nontemporal_load((const f32x4*)(base + off)); }
; #pragma unroll
;                 for (int m = 0; m < 4; ++m)
; #pragma unroll
;                     for (int n = 0; n < 2; ++n) { const size_t off = (size_t)(u.pm * BM + ai * HALF + wr * 64 + m * 16 + fr) * DMODEL + col0 + bj * HALF + n * 16;
;                         *(f32x4*)(out + off) = bsv[m][n] * ALPHA + gvv[bj][n] * acc[ai][bj][m][n]; } }
; __global__ void __launch_bounds__(512, 2) fwd_kernel(Args a) {
;     ...
;             for (int j = 0; j < 8; ++j) { const f32x4 gg = ggv[j], bb = bbv[j];
;                 const f32x4 ya = va[j] * rstd_a * gg + bb, yb = vb[j] * rstd_b * gg + bb; __builtin_nontemporal_store(ya, xr + 64 * j); __builtin_nontemporal_store(yb, xr + 512 + 64 * j);
	v_lshl_add_u64 v[124:125], s[4:5], 0, v[212:213]
	v_lshl_add_u64 v[124:125], v[124:125], 0, v[164:165]
	global_store_dwordx4 v[124:125], v[126:129], off
	s_nop 1
	v_pk_fma_f32 v[188:189], v[150:151], v[172:173], v[188:189] op_sel:[0,1,0] op_sel_hi:[0,1,1]
	v_pk_mul_f32 v[188:189], v[188:189], v[150:151] op_sel:[0,1] op_sel_hi:[1,1]
	v_pk_fma_f32 v[188:189], v[228:229], v[188:189], v[244:245]
	v_pk_fma_f32 v[190:191], v[150:151], v[172:173], v[190:191] op_sel:[0,1,0] op_sel_hi:[0,1,1]
	v_pk_mul_f32 v[190:191], v[190:191], v[150:151] op_sel:[0,1] op_sel_hi:[1,1]
	v_pk_fma_f32 v[190:191], v[230:231], v[190:191], v[246:247]
	v_pk_mul_f32 v[126:127], v[190:191], s[12:13] op_sel_hi:[1,0]
	v_pk_mul_f32 v[128:129], v[188:189], s[12:13] op_sel_hi:[1,0]
	v_pk_fma_f32 v[122:123], v[122:123], v[138:139], v[126:127]
	v_pk_fma_f32 v[120:121], v[120:121], v[136:137], v[128:129]
	global_store_dwordx4 v[124:125], v[120:123], off offset:64
	s_nop 1
	v_pk_fma_f32 v[192:193], v[152:153], v[172:173], v[192:193] op_sel:[0,1,0] op_sel_hi:[0,1,1]
	v_pk_mul_f32 v[192:193], v[192:193], v[152:153] op_sel:[0,1] op_sel_hi:[1,1]
	v_pk_fma_f32 v[192:193], v[224:225], v[192:193], v[240:241]
	v_pk_fma_f32 v[194:195], v[152:153], v[172:173], v[194:195] op_sel:[0,1,0] op_sel_hi:[0,1,1]
	v_pk_mul_f32 v[194:195], v[194:195], v[152:153] op_sel:[0,1] op_sel_hi:[1,1]
	v_pk_fma_f32 v[194:195], v[226:227], v[194:195], v[242:243]
	v_pk_mul_f32 v[120:121], v[194:195], s[12:13] op_sel_hi:[1,0]
	v_pk_mul_f32 v[122:123], v[192:193], s[12:13] op_sel_hi:[1,0]
	v_pk_fma_f32 v[120:121], v[118:119], v[142:143], v[120:121]
	v_pk_fma_f32 v[118:119], v[116:117], v[140:141], v[122:123]
	v_lshl_add_u64 v[116:117], s[4:5], 0, v[214:215]
	v_lshl_add_u64 v[116:117], v[116:117], 0, v[164:165]
	global_store_dwordx4 v[116:117], v[118:121], off
	s_nop 1
	v_pk_fma_f32 v[198:199], v[152:153], v[172:173], v[198:199] op_sel:[0,1,0] op_sel_hi:[0,1,1]
	v_pk_mul_f32 v[198:199], v[198:199], v[152:153] op_sel:[0,1] op_sel_hi:[1,1]
	v_pk_fma_f32 v[198:199], v[228:229], v[198:199], v[244:245]
	v_pk_fma_f32 v[200:201], v[152:153], v[172:173], v[200:201] op_sel:[0,1,0] op_sel_hi:[0,1,1]
	v_pk_mul_f32 v[200:201], v[200:201], v[152:153] op_sel:[0,1] op_sel_hi:[1,1]
	v_pk_fma_f32 v[200:201], v[230:231], v[200:201], v[246:247]
	v_pk_mul_f32 v[118:119], v[200:201], s[12:13] op_sel_hi:[1,0]
	v_pk_mul_f32 v[120:121], v[198:199], s[12:13] op_sel_hi:[1,0]
	v_pk_fma_f32 v[114:115], v[114:115], v[138:139], v[118:119]
	v_pk_fma_f32 v[112:113], v[112:113], v[136:137], v[120:121]
	global_store_dwordx4 v[116:117], v[112:115], off offset:64
	v_pk_fma_f32 v[202:203], v[154:155], v[172:173], v[202:203] op_sel:[0,1,0] op_sel_hi:[0,1,1]
	v_pk_mul_f32 v[202:203], v[202:203], v[154:155] op_sel:[0,1] op_sel_hi:[1,1]
	v_pk_fma_f32 v[202:203], v[224:225], v[202:203], v[240:241]
	v_pk_fma_f32 v[204:205], v[154:155], v[172:173], v[204:205] op_sel:[0,1,0] op_sel_hi:[0,1,1]
	v_pk_mul_f32 v[204:205], v[204:205], v[154:155] op_sel:[0,1] op_sel_hi:[1,1]
	v_pk_fma_f32 v[204:205], v[226:227], v[204:205], v[242:243]
	v_pk_mul_f32 v[118:119], v[202:203], s[12:13] op_sel_hi:[1,0]
	s_nop 0
	v_pk_mul_f32 v[112:113], v[204:205], s[12:13] op_sel_hi:[1,0]
	s_nop 0
	v_pk_fma_f32 v[114:115], v[110:111], v[142:143], v[112:113]
	v_pk_fma_f32 v[112:113], v[108:109], v[140:141], v[118:119]
	v_lshl_add_u64 v[108:109], s[4:5], 0, v[216:217]
	v_lshl_add_u64 v[110:111], v[108:109], 0, v[164:165]
	global_store_dwordx4 v[110:111], v[112:115], off
	v_pk_fma_f32 v[206:207], v[154:155], v[172:173], v[206:207] op_sel:[0,1,0] op_sel_hi:[0,1,1]
	v_pk_mul_f32 v[206:207], v[206:207], v[154:155] op_sel:[0,1] op_sel_hi:[1,1]
	v_pk_fma_f32 v[206:207], v[228:229], v[206:207], v[244:245]
	v_pk_fma_f32 v[208:209], v[154:155], v[172:173], v[208:209] op_sel:[0,1,0] op_sel_hi:[0,1,1]
	v_pk_mul_f32 v[208:209], v[208:209], v[154:155] op_sel:[0,1] op_sel_hi:[1,1]
	v_pk_fma_f32 v[208:209], v[230:231], v[208:209], v[246:247]
	v_pk_mul_f32 v[108:109], v[208:209], s[12:13] op_sel_hi:[1,0]
	s_nop 0
	v_pk_mul_f32 v[112:113], v[206:207], s[12:13] op_sel_hi:[1,0]
	v_pk_fma_f32 v[106:107], v[106:107], v[138:139], v[108:109]
	v_pk_fma_f32 v[104:105], v[104:105], v[136:137], v[112:113]
	global_store_dwordx4 v[110:111], v[104:107], off offset:64
	v_add_u32_e32 v108, 0xa0, v168
	v_ashrrev_i32_e32 v109, 31, v108
	v_add_u32_e32 v104, 0x80, v168
	v_ashrrev_i32_e32 v105, 31, v104
	v_lshlrev_b64 v[114:115], 13, v[104:105]
	v_lshl_add_u64 v[104:105], v[166:167], 0, v[114:115]
	v_add_u32_e32 v106, 0x90, v168
	global_load_dwordx4 v[118:121], v[104:105], off nt
	global_load_dwordx4 v[126:129], v[104:105], off offset:64 nt
	v_ashrrev_i32_e32 v107, 31, v106
	v_lshlrev_b64 v[122:123], 13, v[106:107]
	v_lshl_add_u64 v[106:107], v[166:167], 0, v[122:123]
	global_load_dwordx4 v[176:179], v[106:107], off nt
	global_load_dwordx4 v[180:183], v[106:107], off offset:64 nt
	v_lshlrev_b64 v[130:131], 13, v[108:109]
	v_lshl_add_u64 v[108:109], v[166:167], 0, v[130:131]
	global_load_dwordx4 v[184:187], v[108:109], off nt
	global_load_dwordx4 v[188:191], v[108:109], off offset:64 nt
	v_add_u32_e32 v112, 0xb0, v168
	v_ashrrev_i32_e32 v113, 31, v112
	v_lshlrev_b64 v[134:135], 13, v[112:113]
	v_lshl_add_u64 v[112:113], v[166:167], 0, v[134:135]
	global_load_dwordx4 v[166:169], v[112:113], off nt
	global_load_dwordx4 v[192:195], v[112:113], off offset:64 nt
	s_waitcnt vmcnt(7)
;     __device__ __forceinline__ void operator()(const Acc& acc, const Unit& u, int wr, int wc, int fr, int fq) const {
;     ...
;                 for (int m = 0; m < 4; ++m)
; #pragma unroll
;                     for (int n = 0; n < 2; ++n) { const size_t off = (size_t)(u.pm * BM + ai * HALF + wr * 64 + m * 16 + fr) * DMODEL + col0 + bj * HALF + n * 16; bsv[m][n] = __builtin_nontemporal_load((const f32x4*)(base + off)); }
; #pragma unroll
;                 for (int m = 0; m < 4; ++m)
; #pragma unroll
;                     for (int n = 0; n < 2; ++n) { const size_t off = (size_t)(u.pm * BM + ai * HALF + wr * 64 + m * 16 + fr) * DMODEL + col0 + bj * HALF + n * 16;
;                         *(f32x4*)(out + off) = bsv[m][n] * ALPHA + gvv[bj][n] * acc[ai][bj][m][n]; } }
; __global__ void __launch_bounds__(512, 2) fwd_kernel(Args a) {
;     ...
;             for (int j = 0; j < 8; ++j) { const f32x4 gg = ggv[j], bb = bbv[j];
;                 const f32x4 ya = va[j] * rstd_a * gg + bb, yb = vb[j] * rstd_b * gg + bb; __builtin_nontemporal_store(ya, xr + 64 * j); __builtin_nontemporal_store(yb, xr + 512 + 64 * j);
	v_pk_fma_f32 v[118:119], v[252:253], v[172:173], v[118:119] op_sel:[0,1,0] op_sel_hi:[0,1,1]
	v_pk_mul_f32 v[118:119], v[118:119], v[252:253] op_sel:[0,1] op_sel_hi:[1,1]
	v_pk_fma_f32 v[118:119], v[224:225], v[118:119], v[240:241]
	v_pk_fma_f32 v[120:121], v[252:253], v[172:173], v[120:121] op_sel:[0,1,0] op_sel_hi:[0,1,1]
	v_pk_mul_f32 v[120:121], v[120:121], v[252:253] op_sel:[0,1] op_sel_hi:[1,1]
	v_pk_fma_f32 v[120:121], v[226:227], v[120:121], v[242:243]
	v_pk_mul_f32 v[120:121], v[120:121], s[12:13] op_sel_hi:[1,0]
	v_pk_mul_f32 v[118:119], v[118:119], s[12:13] op_sel_hi:[1,0]
	v_pk_fma_f32 v[120:121], v[102:103], v[142:143], v[120:121]
	v_pk_fma_f32 v[118:119], v[100:101], v[140:141], v[118:119]
	v_lshl_add_u64 v[100:101], s[4:5], 0, v[114:115]
	s_waitcnt vmcnt(6)
	v_pk_fma_f32 v[126:127], v[252:253], v[172:173], v[126:127] op_sel:[0,1,0] op_sel_hi:[0,1,1]
	v_pk_mul_f32 v[126:127], v[126:127], v[252:253] op_sel:[0,1] op_sel_hi:[1,1]
	v_pk_fma_f32 v[126:127], v[228:229], v[126:127], v[244:245]
	v_pk_fma_f32 v[128:129], v[252:253], v[172:173], v[128:129] op_sel:[0,1,0] op_sel_hi:[0,1,1]
	v_pk_mul_f32 v[128:129], v[128:129], v[252:253] op_sel:[0,1] op_sel_hi:[1,1]
	v_pk_fma_f32 v[128:129], v[230:231], v[128:129], v[246:247]
	v_pk_mul_f32 v[102:103], v[128:129], s[12:13] op_sel_hi:[1,0]
	v_pk_mul_f32 v[114:115], v[126:127], s[12:13] op_sel_hi:[1,0]
	v_lshl_add_u64 v[100:101], v[100:101], 0, v[164:165]
	v_pk_fma_f32 v[98:99], v[98:99], v[138:139], v[102:103]
	v_pk_fma_f32 v[96:97], v[96:97], v[136:137], v[114:115]
	global_store_dwordx4 v[100:101], v[96:99], off offset:64
	global_store_dwordx4 v[100:101], v[118:121], off
	s_waitcnt vmcnt(7)
	v_pk_fma_f32 v[176:177], v[174:175], v[172:173], v[176:177] op_sel:[0,1,0] op_sel_hi:[0,1,1]
	v_pk_mul_f32 v[176:177], v[176:177], v[174:175] op_sel:[0,1] op_sel_hi:[1,1]
	v_pk_fma_f32 v[176:177], v[224:225], v[176:177], v[240:241]
	v_pk_fma_f32 v[178:179], v[174:175], v[172:173], v[178:179] op_sel:[0,1,0] op_sel_hi:[0,1,1]
	v_pk_mul_f32 v[178:179], v[178:179], v[174:175] op_sel:[0,1] op_sel_hi:[1,1]
	v_pk_fma_f32 v[178:179], v[226:227], v[178:179], v[242:243]
	v_pk_mul_f32 v[96:97], v[178:179], s[12:13] op_sel_hi:[1,0]
	v_pk_mul_f32 v[98:99], v[176:177], s[12:13] op_sel_hi:[1,0]
	v_pk_fma_f32 v[96:97], v[94:95], v[142:143], v[96:97]
	v_pk_fma_f32 v[94:95], v[92:93], v[140:141], v[98:99]
	v_lshl_add_u64 v[92:93], s[4:5], 0, v[122:123]
	v_lshl_add_u64 v[92:93], v[92:93], 0, v[164:165]
	global_store_dwordx4 v[92:93], v[94:97], off
	s_waitcnt vmcnt(7)
	s_nop 0
	v_pk_fma_f32 v[180:181], v[174:175], v[172:173], v[180:181] op_sel:[0,1,0] op_sel_hi:[0,1,1]
	v_pk_mul_f32 v[180:181], v[180:181], v[174:175] op_sel:[0,1] op_sel_hi:[1,1]
	v_pk_fma_f32 v[180:181], v[228:229], v[180:181], v[244:245]
	v_pk_fma_f32 v[182:183], v[174:175], v[172:173], v[182:183] op_sel:[0,1,0] op_sel_hi:[0,1,1]
	v_pk_mul_f32 v[182:183], v[182:183], v[174:175] op_sel:[0,1] op_sel_hi:[1,1]
	v_pk_fma_f32 v[182:183], v[230:231], v[182:183], v[246:247]
	v_pk_mul_f32 v[94:95], v[182:183], s[12:13] op_sel_hi:[1,0]
	v_pk_mul_f32 v[96:97], v[180:181], s[12:13] op_sel_hi:[1,0]
	v_pk_fma_f32 v[90:91], v[90:91], v[138:139], v[94:95]
	v_pk_fma_f32 v[88:89], v[88:89], v[136:137], v[96:97]
	global_store_dwordx4 v[92:93], v[88:91], off offset:64
	s_waitcnt vmcnt(7)
	s_nop 0
	v_pk_fma_f32 v[184:185], v[222:223], v[172:173], v[184:185] op_sel:[0,1,0] op_sel_hi:[0,1,1]
	v_pk_mul_f32 v[184:185], v[184:185], v[222:223] op_sel:[0,1] op_sel_hi:[1,1]
	v_pk_fma_f32 v[184:185], v[224:225], v[184:185], v[240:241]
	v_pk_fma_f32 v[186:187], v[222:223], v[172:173], v[186:187] op_sel:[0,1,0] op_sel_hi:[0,1,1]
	v_pk_mul_f32 v[186:187], v[186:187], v[222:223] op_sel:[0,1] op_sel_hi:[1,1]
	v_pk_fma_f32 v[186:187], v[226:227], v[186:187], v[242:243]
	v_pk_mul_f32 v[88:89], v[186:187], s[12:13] op_sel_hi:[1,0]
	v_pk_mul_f32 v[90:91], v[184:185], s[12:13] op_sel_hi:[1,0]
	v_pk_fma_f32 v[88:89], v[86:87], v[142:143], v[88:89]
	v_pk_fma_f32 v[86:87], v[84:85], v[140:141], v[90:91]
	v_lshl_add_u64 v[84:85], s[4:5], 0, v[130:131]
	v_lshl_add_u64 v[84:85], v[84:85], 0, v[164:165]
	global_store_dwordx4 v[84:85], v[86:89], off
	s_waitcnt vmcnt(7)
	s_nop 0
	v_pk_fma_f32 v[188:189], v[222:223], v[172:173], v[188:189] op_sel:[0,1,0] op_sel_hi:[0,1,1]
	v_pk_mul_f32 v[188:189], v[188:189], v[222:223] op_sel:[0,1] op_sel_hi:[1,1]
	v_pk_fma_f32 v[188:189], v[228:229], v[188:189], v[244:245]
	v_pk_fma_f32 v[190:191], v[222:223], v[172:173], v[190:191] op_sel:[0,1,0] op_sel_hi:[0,1,1]
	v_pk_mul_f32 v[190:191], v[190:191], v[222:223] op_sel:[0,1] op_sel_hi:[1,1]
	v_pk_fma_f32 v[190:191], v[230:231], v[190:191], v[246:247]
	v_pk_mul_f32 v[86:87], v[190:191], s[12:13] op_sel_hi:[1,0]
	v_pk_mul_f32 v[88:89], v[188:189], s[12:13] op_sel_hi:[1,0]
	v_pk_fma_f32 v[82:83], v[82:83], v[138:139], v[86:87]
	v_pk_fma_f32 v[80:81], v[80:81], v[136:137], v[88:89]
	global_store_dwordx4 v[84:85], v[80:83], off offset:64
	s_waitcnt vmcnt(7)
	s_nop 0
	v_pk_fma_f32 v[166:167], v[220:221], v[172:173], v[166:167] op_sel:[0,1,0] op_sel_hi:[0,1,1]
	v_pk_mul_f32 v[166:167], v[166:167], v[220:221] op_sel:[0,1] op_sel_hi:[1,1]
	v_pk_fma_f32 v[166:167], v[224:225], v[166:167], v[240:241]
	v_pk_fma_f32 v[168:169], v[220:221], v[172:173], v[168:169] op_sel:[0,1,0] op_sel_hi:[0,1,1]
	v_pk_mul_f32 v[168:169], v[168:169], v[220:221] op_sel:[0,1] op_sel_hi:[1,1]
	v_pk_fma_f32 v[168:169], v[226:227], v[168:169], v[242:243]
	v_pk_mul_f32 v[80:81], v[168:169], s[12:13] op_sel_hi:[1,0]
	v_pk_mul_f32 v[82:83], v[166:167], s[12:13] op_sel_hi:[1,0]
	v_pk_fma_f32 v[80:81], v[78:79], v[142:143], v[80:81]
	v_pk_fma_f32 v[78:79], v[76:77], v[140:141], v[82:83]
	v_lshl_add_u64 v[76:77], s[4:5], 0, v[134:135]
	v_lshl_add_u64 v[76:77], v[76:77], 0, v[164:165]
	global_store_dwordx4 v[76:77], v[78:81], off
	s_waitcnt vmcnt(7)
;     __device__ __forceinline__ void operator()(const Acc& acc, const Unit& u, int wr, int wc, int fr, int fq) const {
;     ...
;                 for (int m = 0; m < 4; ++m)
; #pragma unroll
;                     for (int n = 0; n < 2; ++n) { const size_t off = (size_t)(u.pm * BM + ai * HALF + wr * 64 + m * 16 + fr) * DMODEL + col0 + bj * HALF + n * 16; bsv[m][n] = __builtin_nontemporal_load((const f32x4*)(base + off)); }
; #pragma unroll
;                 for (int m = 0; m < 4; ++m)
; #pragma unroll
;                     for (int n = 0; n < 2; ++n) { const size_t off = (size_t)(u.pm * BM + ai * HALF + wr * 64 + m * 16 + fr) * DMODEL + col0 + bj * HALF + n * 16;
;                         *(f32x4*)(out + off) = bsv[m][n] * ALPHA + gvv[bj][n] * acc[ai][bj][m][n]; } }
; __global__ void __launch_bounds__(512, 2) fwd_kernel(Args a) {
;     ...
;             for (int j = 0; j < 8; ++j) { const f32x4 gg = ggv[j], bb = bbv[j];
;                 const f32x4 ya = va[j] * rstd_a * gg + bb, yb = vb[j] * rstd_b * gg + bb; __builtin_nontemporal_store(ya, xr + 64 * j); __builtin_nontemporal_store(yb, xr + 512 + 64 * j);
	s_nop 0
	v_pk_fma_f32 v[192:193], v[220:221], v[172:173], v[192:193] op_sel:[0,1,0] op_sel_hi:[0,1,1]
	v_pk_mul_f32 v[192:193], v[192:193], v[220:221] op_sel:[0,1] op_sel_hi:[1,1]
	v_pk_fma_f32 v[192:193], v[228:229], v[192:193], v[244:245]
	v_pk_fma_f32 v[194:195], v[220:221], v[172:173], v[194:195] op_sel:[0,1,0] op_sel_hi:[0,1,1]
	v_pk_mul_f32 v[194:195], v[194:195], v[220:221] op_sel:[0,1] op_sel_hi:[1,1]
	v_pk_fma_f32 v[194:195], v[230:231], v[194:195], v[246:247]
	v_pk_mul_f32 v[78:79], v[194:195], s[12:13] op_sel_hi:[1,0]
	v_pk_mul_f32 v[80:81], v[192:193], s[12:13] op_sel_hi:[1,0]
	v_pk_fma_f32 v[74:75], v[74:75], v[138:139], v[78:79]
	v_pk_fma_f32 v[72:73], v[72:73], v[136:137], v[80:81]
	global_store_dwordx4 v[76:77], v[72:75], off offset:64
	global_load_dwordx4 v[72:75], v[162:163], off offset:512 nt
	s_nop 0
	global_load_dwordx4 v[78:81], v[162:163], off offset:576 nt
	global_load_dwordx4 v[86:89], v[160:161], off offset:512 nt
	global_load_dwordx4 v[94:97], v[160:161], off offset:576 nt
	global_load_dwordx4 v[118:121], v[158:159], off offset:512 nt
	global_load_dwordx4 v[126:129], v[158:159], off offset:576 nt
	global_load_dwordx4 v[134:137], v[156:157], off offset:512 nt
	global_load_dwordx4 v[138:141], v[156:157], off offset:576 nt
	s_waitcnt vmcnt(7)
	v_pk_fma_f32 v[72:73], v[148:149], v[172:173], v[72:73] op_sel:[0,1,0] op_sel_hi:[0,1,1]
	v_pk_mul_f32 v[72:73], v[72:73], v[148:149] op_sel:[0,1] op_sel_hi:[1,1]
	v_pk_fma_f32 v[72:73], v[232:233], v[72:73], v[248:249]
	v_pk_fma_f32 v[74:75], v[148:149], v[172:173], v[74:75] op_sel:[0,1,0] op_sel_hi:[0,1,1]
	v_pk_mul_f32 v[74:75], v[74:75], v[148:149] op_sel:[0,1] op_sel_hi:[1,1]
	v_pk_fma_f32 v[74:75], v[234:235], v[74:75], v[250:251]
	v_pk_mul_f32 v[74:75], v[74:75], s[12:13] op_sel_hi:[1,0]
	v_pk_mul_f32 v[72:73], v[72:73], s[12:13] op_sel_hi:[1,0]
	v_pk_fma_f32 v[62:63], v[62:63], v[70:71], v[74:75]
	v_pk_fma_f32 v[60:61], v[60:61], v[68:69], v[72:73]
	global_store_dwordx4 v[132:133], v[60:63], off offset:512
	s_waitcnt vmcnt(7)
	s_nop 0
	v_pk_fma_f32 v[78:79], v[148:149], v[172:173], v[78:79] op_sel:[0,1,0] op_sel_hi:[0,1,1]
	v_pk_mul_f32 v[78:79], v[78:79], v[148:149] op_sel:[0,1] op_sel_hi:[1,1]
	v_pk_fma_f32 v[78:79], v[236:237], v[78:79], v[144:145]
	v_pk_fma_f32 v[80:81], v[148:149], v[172:173], v[80:81] op_sel:[0,1,0] op_sel_hi:[0,1,1]
	v_pk_mul_f32 v[80:81], v[80:81], v[148:149] op_sel:[0,1] op_sel_hi:[1,1]
	v_pk_fma_f32 v[80:81], v[238:239], v[80:81], v[146:147]
	v_pk_mul_f32 v[60:61], v[80:81], s[12:13] op_sel_hi:[1,0]
	v_pk_mul_f32 v[62:63], v[78:79], s[12:13] op_sel_hi:[1,0]
	v_pk_fma_f32 v[58:59], v[58:59], v[66:67], v[60:61]
	v_pk_fma_f32 v[56:57], v[56:57], v[64:65], v[62:63]
	global_store_dwordx4 v[132:133], v[56:59], off offset:576
	s_waitcnt vmcnt(7)
	s_nop 0
	v_pk_fma_f32 v[86:87], v[150:151], v[172:173], v[86:87] op_sel:[0,1,0] op_sel_hi:[0,1,1]
	v_pk_mul_f32 v[86:87], v[86:87], v[150:151] op_sel:[0,1] op_sel_hi:[1,1]
	v_pk_fma_f32 v[86:87], v[232:233], v[86:87], v[248:249]
	v_pk_fma_f32 v[88:89], v[150:151], v[172:173], v[88:89] op_sel:[0,1,0] op_sel_hi:[0,1,1]
	v_pk_mul_f32 v[88:89], v[88:89], v[150:151] op_sel:[0,1] op_sel_hi:[1,1]
	v_pk_fma_f32 v[88:89], v[234:235], v[88:89], v[250:251]
	v_pk_mul_f32 v[56:57], v[88:89], s[12:13] op_sel_hi:[1,0]
	v_pk_mul_f32 v[58:59], v[86:87], s[12:13] op_sel_hi:[1,0]
	v_pk_fma_f32 v[54:55], v[54:55], v[70:71], v[56:57]
	v_pk_fma_f32 v[52:53], v[52:53], v[68:69], v[58:59]
	global_store_dwordx4 v[124:125], v[52:55], off offset:512
	s_waitcnt vmcnt(7)
	s_nop 0
	v_pk_fma_f32 v[94:95], v[150:151], v[172:173], v[94:95] op_sel:[0,1,0] op_sel_hi:[0,1,1]
	v_pk_mul_f32 v[94:95], v[94:95], v[150:151] op_sel:[0,1] op_sel_hi:[1,1]
	v_pk_fma_f32 v[94:95], v[236:237], v[94:95], v[144:145]
	v_pk_fma_f32 v[96:97], v[150:151], v[172:173], v[96:97] op_sel:[0,1,0] op_sel_hi:[0,1,1]
	v_pk_mul_f32 v[96:97], v[96:97], v[150:151] op_sel:[0,1] op_sel_hi:[1,1]
	v_pk_fma_f32 v[96:97], v[238:239], v[96:97], v[146:147]
	v_pk_mul_f32 v[52:53], v[96:97], s[12:13] op_sel_hi:[1,0]
	v_pk_mul_f32 v[54:55], v[94:95], s[12:13] op_sel_hi:[1,0]
	v_pk_fma_f32 v[50:51], v[50:51], v[66:67], v[52:53]
	v_pk_fma_f32 v[48:49], v[48:49], v[64:65], v[54:55]
	global_store_dwordx4 v[124:125], v[48:51], off offset:576
	s_waitcnt vmcnt(7)
	s_nop 0
	v_pk_fma_f32 v[118:119], v[152:153], v[172:173], v[118:119] op_sel:[0,1,0] op_sel_hi:[0,1,1]
	v_pk_mul_f32 v[118:119], v[118:119], v[152:153] op_sel:[0,1] op_sel_hi:[1,1]
	v_pk_fma_f32 v[118:119], v[232:233], v[118:119], v[248:249]
	v_pk_fma_f32 v[120:121], v[152:153], v[172:173], v[120:121] op_sel:[0,1,0] op_sel_hi:[0,1,1]
	v_pk_mul_f32 v[120:121], v[120:121], v[152:153] op_sel:[0,1] op_sel_hi:[1,1]
	v_pk_fma_f32 v[120:121], v[234:235], v[120:121], v[250:251]
	v_pk_mul_f32 v[48:49], v[120:121], s[12:13] op_sel_hi:[1,0]
	v_pk_mul_f32 v[50:51], v[118:119], s[12:13] op_sel_hi:[1,0]
	v_pk_fma_f32 v[46:47], v[46:47], v[70:71], v[48:49]
	v_pk_fma_f32 v[44:45], v[44:45], v[68:69], v[50:51]
	global_store_dwordx4 v[116:117], v[44:47], off offset:512
	s_waitcnt vmcnt(7)
	s_nop 0
	v_pk_fma_f32 v[126:127], v[152:153], v[172:173], v[126:127] op_sel:[0,1,0] op_sel_hi:[0,1,1]
	v_pk_mul_f32 v[126:127], v[126:127], v[152:153] op_sel:[0,1] op_sel_hi:[1,1]
	v_pk_fma_f32 v[126:127], v[236:237], v[126:127], v[144:145]
	v_pk_fma_f32 v[128:129], v[152:153], v[172:173], v[128:129] op_sel:[0,1,0] op_sel_hi:[0,1,1]
	v_pk_mul_f32 v[128:129], v[128:129], v[152:153] op_sel:[0,1] op_sel_hi:[1,1]
	v_pk_fma_f32 v[128:129], v[238:239], v[128:129], v[146:147]
	v_pk_mul_f32 v[44:45], v[128:129], s[12:13] op_sel_hi:[1,0]
	v_pk_mul_f32 v[46:47], v[126:127], s[12:13] op_sel_hi:[1,0]
	v_pk_fma_f32 v[42:43], v[42:43], v[66:67], v[44:45]
	v_pk_fma_f32 v[40:41], v[40:41], v[64:65], v[46:47]
	global_store_dwordx4 v[116:117], v[40:43], off offset:576
	s_waitcnt vmcnt(7)
;     __device__ __forceinline__ void operator()(const Acc& acc, const Unit& u, int wr, int wc, int fr, int fq) const {
;     ...
;                 for (int m = 0; m < 4; ++m)
; #pragma unroll
;                     for (int n = 0; n < 2; ++n) { const size_t off = (size_t)(u.pm * BM + ai * HALF + wr * 64 + m * 16 + fr) * DMODEL + col0 + bj * HALF + n * 16; bsv[m][n] = __builtin_nontemporal_load((const f32x4*)(base + off)); }
; #pragma unroll
;                 for (int m = 0; m < 4; ++m)
; #pragma unroll
;                     for (int n = 0; n < 2; ++n) { const size_t off = (size_t)(u.pm * BM + ai * HALF + wr * 64 + m * 16 + fr) * DMODEL + col0 + bj * HALF + n * 16;
;                         *(f32x4*)(out + off) = bsv[m][n] * ALPHA + gvv[bj][n] * acc[ai][bj][m][n]; } }
; __global__ void __launch_bounds__(512, 2) fwd_kernel(Args a) {
;     ...
;             for (int j = 0; j < 8; ++j) { const f32x4 gg = ggv[j], bb = bbv[j];
;                 const f32x4 ya = va[j] * rstd_a * gg + bb, yb = vb[j] * rstd_b * gg + bb; __builtin_nontemporal_store(ya, xr + 64 * j); __builtin_nontemporal_store(yb, xr + 512 + 64 * j);
	s_nop 0
	v_pk_fma_f32 v[134:135], v[154:155], v[172:173], v[134:135] op_sel:[0,1,0] op_sel_hi:[0,1,1]
	v_pk_mul_f32 v[134:135], v[134:135], v[154:155] op_sel:[0,1] op_sel_hi:[1,1]
	v_pk_fma_f32 v[134:135], v[232:233], v[134:135], v[248:249]
	v_pk_fma_f32 v[136:137], v[154:155], v[172:173], v[136:137] op_sel:[0,1,0] op_sel_hi:[0,1,1]
	v_pk_mul_f32 v[136:137], v[136:137], v[154:155] op_sel:[0,1] op_sel_hi:[1,1]
	v_pk_fma_f32 v[136:137], v[234:235], v[136:137], v[250:251]
	v_pk_mul_f32 v[40:41], v[136:137], s[12:13] op_sel_hi:[1,0]
	v_pk_mul_f32 v[42:43], v[134:135], s[12:13] op_sel_hi:[1,0]
	v_pk_fma_f32 v[38:39], v[38:39], v[70:71], v[40:41]
	v_pk_fma_f32 v[36:37], v[36:37], v[68:69], v[42:43]
	global_store_dwordx4 v[110:111], v[36:39], off offset:512
	s_waitcnt vmcnt(7)
	s_nop 0
	v_pk_fma_f32 v[138:139], v[154:155], v[172:173], v[138:139] op_sel:[0,1,0] op_sel_hi:[0,1,1]
	v_pk_mul_f32 v[138:139], v[138:139], v[154:155] op_sel:[0,1] op_sel_hi:[1,1]
	v_pk_fma_f32 v[138:139], v[236:237], v[138:139], v[144:145]
	v_pk_fma_f32 v[140:141], v[154:155], v[172:173], v[140:141] op_sel:[0,1,0] op_sel_hi:[0,1,1]
	v_pk_mul_f32 v[140:141], v[140:141], v[154:155] op_sel:[0,1] op_sel_hi:[1,1]
	v_pk_fma_f32 v[140:141], v[238:239], v[140:141], v[146:147]
	v_pk_mul_f32 v[36:37], v[140:141], s[12:13] op_sel_hi:[1,0]
	v_pk_mul_f32 v[38:39], v[138:139], s[12:13] op_sel_hi:[1,0]
	v_pk_fma_f32 v[34:35], v[34:35], v[66:67], v[36:37]
	v_pk_fma_f32 v[32:33], v[32:33], v[64:65], v[38:39]
	global_store_dwordx4 v[110:111], v[32:35], off offset:576
	global_load_dwordx4 v[32:35], v[104:105], off offset:512 nt
	s_nop 0
	global_load_dwordx4 v[36:39], v[104:105], off offset:576 nt
	global_load_dwordx4 v[40:43], v[106:107], off offset:512 nt
	global_load_dwordx4 v[44:47], v[106:107], off offset:576 nt
	global_load_dwordx4 v[48:51], v[108:109], off offset:512 nt
	global_load_dwordx4 v[52:55], v[108:109], off offset:576 nt
	global_load_dwordx4 v[56:59], v[112:113], off offset:512 nt
	global_load_dwordx4 v[60:63], v[112:113], off offset:576 nt
	s_waitcnt vmcnt(7)
	v_pk_fma_f32 v[32:33], v[252:253], v[172:173], v[32:33] op_sel:[0,1,0] op_sel_hi:[0,1,1]
	v_pk_mul_f32 v[32:33], v[32:33], v[252:253] op_sel:[0,1] op_sel_hi:[1,1]
	v_pk_fma_f32 v[32:33], v[232:233], v[32:33], v[248:249]
	v_pk_fma_f32 v[34:35], v[252:253], v[172:173], v[34:35] op_sel:[0,1,0] op_sel_hi:[0,1,1]
	v_pk_mul_f32 v[34:35], v[34:35], v[252:253] op_sel:[0,1] op_sel_hi:[1,1]
	v_pk_fma_f32 v[34:35], v[234:235], v[34:35], v[250:251]
	v_pk_mul_f32 v[34:35], v[34:35], s[12:13] op_sel_hi:[1,0]
	v_pk_mul_f32 v[32:33], v[32:33], s[12:13] op_sel_hi:[1,0]
	v_pk_fma_f32 v[30:31], v[30:31], v[70:71], v[34:35]
	v_pk_fma_f32 v[28:29], v[28:29], v[68:69], v[32:33]
	global_store_dwordx4 v[100:101], v[28:31], off offset:512
	s_waitcnt vmcnt(7)
	s_nop 0
	v_pk_fma_f32 v[36:37], v[252:253], v[172:173], v[36:37] op_sel:[0,1,0] op_sel_hi:[0,1,1]
	v_pk_mul_f32 v[36:37], v[36:37], v[252:253] op_sel:[0,1] op_sel_hi:[1,1]
	v_pk_fma_f32 v[36:37], v[236:237], v[36:37], v[144:145]
	v_pk_fma_f32 v[38:39], v[252:253], v[172:173], v[38:39] op_sel:[0,1,0] op_sel_hi:[0,1,1]
	v_pk_mul_f32 v[38:39], v[38:39], v[252:253] op_sel:[0,1] op_sel_hi:[1,1]
	v_pk_fma_f32 v[38:39], v[238:239], v[38:39], v[146:147]
	v_pk_mul_f32 v[28:29], v[38:39], s[12:13] op_sel_hi:[1,0]
	v_pk_mul_f32 v[30:31], v[36:37], s[12:13] op_sel_hi:[1,0]
	v_pk_fma_f32 v[26:27], v[26:27], v[66:67], v[28:29]
	v_pk_fma_f32 v[24:25], v[24:25], v[64:65], v[30:31]
	global_store_dwordx4 v[100:101], v[24:27], off offset:576
	s_waitcnt vmcnt(7)
	s_nop 0
	v_pk_fma_f32 v[40:41], v[174:175], v[172:173], v[40:41] op_sel:[0,1,0] op_sel_hi:[0,1,1]
	v_pk_mul_f32 v[40:41], v[40:41], v[174:175] op_sel:[0,1] op_sel_hi:[1,1]
	v_pk_fma_f32 v[40:41], v[232:233], v[40:41], v[248:249]
	v_pk_fma_f32 v[42:43], v[174:175], v[172:173], v[42:43] op_sel:[0,1,0] op_sel_hi:[0,1,1]
	v_pk_mul_f32 v[42:43], v[42:43], v[174:175] op_sel:[0,1] op_sel_hi:[1,1]
	v_pk_fma_f32 v[42:43], v[234:235], v[42:43], v[250:251]
	v_pk_mul_f32 v[24:25], v[42:43], s[12:13] op_sel_hi:[1,0]
	v_pk_mul_f32 v[26:27], v[40:41], s[12:13] op_sel_hi:[1,0]
	v_pk_fma_f32 v[22:23], v[22:23], v[70:71], v[24:25]
	v_pk_fma_f32 v[20:21], v[20:21], v[68:69], v[26:27]
	global_store_dwordx4 v[92:93], v[20:23], off offset:512
	s_waitcnt vmcnt(7)
;     __device__ __forceinline__ void operator()(const Acc& acc, const Unit& u, int wr, int wc, int fr, int fq) const {
;     ...
;                 for (int m = 0; m < 4; ++m)
; #pragma unroll
;                     for (int n = 0; n < 2; ++n) { const size_t off = (size_t)(u.pm * BM + ai * HALF + wr * 64 + m * 16 + fr) * DMODEL + col0 + bj * HALF + n * 16; bsv[m][n] = __builtin_nontemporal_load((const f32x4*)(base + off)); }
; #pragma unroll
;                 for (int m = 0; m < 4; ++m)
; #pragma unroll
;                     for (int n = 0; n < 2; ++n) { const size_t off = (size_t)(u.pm * BM + ai * HALF + wr * 64 + m * 16 + fr) * DMODEL + col0 + bj * HALF + n * 16;
;                         *(f32x4*)(out + off) = bsv[m][n] * ALPHA + gvv[bj][n] * acc[ai][bj][m][n]; } }
; __global__ void __launch_bounds__(512, 2) fwd_kernel(Args a) {
;     ...
;             for (int j = 0; j < 8; ++j) { const f32x4 gg = ggv[j], bb = bbv[j];
;                 const f32x4 ya = va[j] * rstd_a * gg + bb, yb = vb[j] * rstd_b * gg + bb; __builtin_nontemporal_store(ya, xr + 64 * j); __builtin_nontemporal_store(yb, xr + 512 + 64 * j);
	s_nop 0
	v_pk_fma_f32 v[44:45], v[174:175], v[172:173], v[44:45] op_sel:[0,1,0] op_sel_hi:[0,1,1]
	v_pk_mul_f32 v[44:45], v[44:45], v[174:175] op_sel:[0,1] op_sel_hi:[1,1]
	v_pk_fma_f32 v[44:45], v[236:237], v[44:45], v[144:145]
	v_pk_fma_f32 v[46:47], v[174:175], v[172:173], v[46:47] op_sel:[0,1,0] op_sel_hi:[0,1,1]
	v_pk_mul_f32 v[46:47], v[46:47], v[174:175] op_sel:[0,1] op_sel_hi:[1,1]
	v_pk_fma_f32 v[46:47], v[238:239], v[46:47], v[146:147]
	v_pk_mul_f32 v[20:21], v[46:47], s[12:13] op_sel_hi:[1,0]
	v_pk_mul_f32 v[22:23], v[44:45], s[12:13] op_sel_hi:[1,0]
	v_pk_fma_f32 v[18:19], v[18:19], v[66:67], v[20:21]
	v_pk_fma_f32 v[16:17], v[16:17], v[64:65], v[22:23]
	global_store_dwordx4 v[92:93], v[16:19], off offset:576
	s_waitcnt vmcnt(7)
	s_nop 0
	v_pk_fma_f32 v[48:49], v[222:223], v[172:173], v[48:49] op_sel:[0,1,0] op_sel_hi:[0,1,1]
	v_pk_mul_f32 v[48:49], v[48:49], v[222:223] op_sel:[0,1] op_sel_hi:[1,1]
	v_pk_fma_f32 v[48:49], v[232:233], v[48:49], v[248:249]
	v_pk_fma_f32 v[50:51], v[222:223], v[172:173], v[50:51] op_sel:[0,1,0] op_sel_hi:[0,1,1]
	v_pk_mul_f32 v[50:51], v[50:51], v[222:223] op_sel:[0,1] op_sel_hi:[1,1]
	v_pk_fma_f32 v[50:51], v[234:235], v[50:51], v[250:251]
	v_pk_mul_f32 v[16:17], v[50:51], s[12:13] op_sel_hi:[1,0]
	v_pk_mul_f32 v[18:19], v[48:49], s[12:13] op_sel_hi:[1,0]
	v_pk_fma_f32 v[14:15], v[14:15], v[70:71], v[16:17]
	v_pk_fma_f32 v[12:13], v[12:13], v[68:69], v[18:19]
	global_store_dwordx4 v[84:85], v[12:15], off offset:512
	s_waitcnt vmcnt(7)
	s_nop 0
	v_pk_fma_f32 v[52:53], v[222:223], v[172:173], v[52:53] op_sel:[0,1,0] op_sel_hi:[0,1,1]
	v_pk_mul_f32 v[52:53], v[52:53], v[222:223] op_sel:[0,1] op_sel_hi:[1,1]
	v_pk_fma_f32 v[52:53], v[236:237], v[52:53], v[144:145]
	v_pk_fma_f32 v[54:55], v[222:223], v[172:173], v[54:55] op_sel:[0,1,0] op_sel_hi:[0,1,1]
	v_pk_mul_f32 v[54:55], v[54:55], v[222:223] op_sel:[0,1] op_sel_hi:[1,1]
	v_pk_fma_f32 v[54:55], v[238:239], v[54:55], v[146:147]
	v_pk_mul_f32 v[12:13], v[54:55], s[12:13] op_sel_hi:[1,0]
	v_pk_mul_f32 v[14:15], v[52:53], s[12:13] op_sel_hi:[1,0]
	v_pk_fma_f32 v[10:11], v[10:11], v[66:67], v[12:13]
	v_pk_fma_f32 v[8:9], v[8:9], v[64:65], v[14:15]
	global_store_dwordx4 v[84:85], v[8:11], off offset:576
	s_waitcnt vmcnt(7)
	s_nop 0
	v_pk_fma_f32 v[56:57], v[220:221], v[172:173], v[56:57] op_sel:[0,1,0] op_sel_hi:[0,1,1]
	v_pk_mul_f32 v[56:57], v[56:57], v[220:221] op_sel:[0,1] op_sel_hi:[1,1]
	v_pk_fma_f32 v[56:57], v[232:233], v[56:57], v[248:249]
	v_pk_fma_f32 v[58:59], v[220:221], v[172:173], v[58:59] op_sel:[0,1,0] op_sel_hi:[0,1,1]
	v_pk_mul_f32 v[58:59], v[58:59], v[220:221] op_sel:[0,1] op_sel_hi:[1,1]
	v_pk_fma_f32 v[58:59], v[234:235], v[58:59], v[250:251]
	v_pk_mul_f32 v[8:9], v[58:59], s[12:13] op_sel_hi:[1,0]
	v_pk_mul_f32 v[10:11], v[56:57], s[12:13] op_sel_hi:[1,0]
	v_pk_fma_f32 v[6:7], v[6:7], v[70:71], v[8:9]
	v_pk_fma_f32 v[4:5], v[4:5], v[68:69], v[10:11]
	global_store_dwordx4 v[76:77], v[4:7], off offset:512
	s_waitcnt vmcnt(7)
	s_nop 0
	v_pk_fma_f32 v[60:61], v[220:221], v[172:173], v[60:61] op_sel:[0,1,0] op_sel_hi:[0,1,1]
	v_pk_mul_f32 v[60:61], v[60:61], v[220:221] op_sel:[0,1] op_sel_hi:[1,1]
	v_pk_fma_f32 v[60:61], v[236:237], v[60:61], v[144:145]
	v_pk_fma_f32 v[62:63], v[220:221], v[172:173], v[62:63] op_sel:[0,1,0] op_sel_hi:[0,1,1]
	v_pk_mul_f32 v[62:63], v[62:63], v[220:221] op_sel:[0,1] op_sel_hi:[1,1]
	v_pk_fma_f32 v[62:63], v[238:239], v[62:63], v[146:147]
	v_pk_mul_f32 v[4:5], v[62:63], s[12:13] op_sel_hi:[1,0]
	v_pk_mul_f32 v[6:7], v[60:61], s[12:13] op_sel_hi:[1,0]
	v_pk_fma_f32 v[2:3], v[2:3], v[66:67], v[4:5]
	v_pk_fma_f32 v[0:1], v[0:1], v[64:65], v[6:7]
	global_store_dwordx4 v[76:77], v[0:3], off offset:576
	s_cbranch_vccnz .LBB0_1091
	s_andn2_b64 vcc, exec, s[6:7]
	s_cbranch_vccnz .LBB0_1090
	s_barrier
	s_branch .LBB0_1090
